# phase 10: score rows fetched with two 16-byte-per-lane loads per sort group and transposed through a per-wave LDS tile (was 16 two-byte loads per thread); plus earlier phase 11a rewrite and 11b addres
# speedup vs baseline: 1.0118x; 1.0046x over previous
; DI void topk_half(const _Float16* __restrict__ sp, unsigned (&R)[16]) {
; #pragma unroll
;   for (int e = 0; e < 16; ++e) R[e] = 0u;
; #pragma unroll 1
;   for (int gi = 0; gi < 8; ++gi) {
;     unsigned Gk[16];
; #pragma unroll
;     for (int e = 0; e < 16; ++e) {
;       const int n = gi * 16 + e;
;       const unsigned bits = __builtin_bit_cast(unsigned short, sp[(long)n * NTOK]);
;       const unsigned o = (bits & 0x8000u) ? (~bits & 0xffffu) : (bits | 0x8000u);
;       Gk[e] = (o << 16) | (unsigned)(127 - n);
;     }
.LBB0_1183:
	v_alignbit_b32 v1, v129, v128, 15
	v_lshlrev_b32_e32 v4, 1, v1
	v_ashrrev_i32_e32 v5, 31, v4
	v_lshlrev_b64 v[4:5], 23, v[4:5]
	v_and_b32_e32 v1, 0x7fff, v26
	v_lshrrev_b64 v[2:3], 15, v[128:129]
	v_lshl_or_b32 v4, v1, 1, v4
	v_lshl_add_u64 v[6:7], s[40:41], 0, v[4:5]
	s_movk_i32 s91, 0x70
	v_mov_b32_e32 v35, 0
	v_mov_b32_e32 v24, 0
	v_mov_b32_e32 v40, 0
	v_mov_b32_e32 v41, 0
	v_mov_b32_e32 v39, 0
	v_mov_b32_e32 v25, 0
	v_mov_b32_e32 v38, 0
	v_mov_b32_e32 v36, 0
	v_mov_b32_e32 v33, 0
	v_mov_b32_e32 v32, 0
	v_mov_b32_e32 v31, 0
	v_mov_b32_e32 v30, 0
	v_mov_b32_e32 v3, 0
	v_mov_b32_e32 v1, 0
	v_mov_b32_e32 v34, 0
	v_mov_b32_e32 v37, 0
	v_lshrrev_b32_e32 v88, 3, v208
	v_and_b32_e32 v89, 7, v208
	v_lshlrev_b32_e32 v88, 16, v88
	v_lshl_add_u32 v88, v89, 4, v88
	v_lshlrev_b32_e32 v89, 1, v208
	v_sub_u32_e32 v88, v88, v89
	v_add_u32_e32 v86, v4, v88
	v_and_b32_e32 v100, 0x3c00, v209
	v_lshlrev_b32_e32 v100, 1, v100
	v_add_u32_e32 v101, v100, v89
	v_lshl_add_u32 v100, v208, 4, v100
.LBB0_1184:
	global_load_dwordx4 v[90:93], v86, s[40:41]
	v_add_u32_e32 v87, 0x80000, v86
	global_load_dwordx4 v[94:97], v87, s[40:41]
	v_add_u32_e32 v86, 0x100000, v86
	s_waitcnt vmcnt(0)
	ds_write_b128 v100, v[90:93]
	ds_write_b128 v100, v[94:97] offset:1024
	s_waitcnt lgkmcnt(0)
	ds_read_u16 v42, v101
	ds_read_u16 v47, v101 offset:128
	ds_read_u16 v46, v101 offset:256
	ds_read_u16 v45, v101 offset:384
	ds_read_u16 v44, v101 offset:512
	ds_read_u16 v43, v101 offset:640
	ds_read_u16 v17, v101 offset:768
	ds_read_u16 v16, v101 offset:896
	ds_read_u16 v14, v101 offset:1024
	ds_read_u16 v13, v101 offset:1152
	ds_read_u16 v12, v101 offset:1280
	ds_read_u16 v11, v101 offset:1408
	ds_read_u16 v10, v101 offset:1536
	ds_read_u16 v9, v101 offset:1664
	ds_read_u16 v8, v101 offset:1792
	ds_read_u16 v15, v101 offset:1920
	s_waitcnt lgkmcnt(0)
	v_and_b32_e32 v18, 0xffff, v42
	v_bitop3_b32 v19, v18, s57, v18 bitop3:0xc
	v_or_b32_e32 v18, 0x8000, v18
	v_cmp_gt_i16_e32 vcc, 0, v42
	v_and_b32_e32 v20, 0xffff, v47
	v_and_b32_e32 v21, 0xffff, v46
	v_and_b32_e32 v22, 0xffff, v45
	v_and_b32_e32 v23, 0xffff, v44
	v_and_b32_e32 v48, 0xffff, v43
	v_and_b32_e32 v49, 0xffff, v17
	v_and_b32_e32 v50, 0xffff, v16
	v_and_b32_e32 v51, 0xffff, v14
	v_and_b32_e32 v52, 0xffff, v13
	v_and_b32_e32 v53, 0xffff, v12
	v_and_b32_e32 v54, 0xffff, v11
	v_and_b32_e32 v55, 0xffff, v10
	v_and_b32_e32 v56, 0xffff, v9
	v_and_b32_e32 v57, 0xffff, v8
	v_and_b32_e32 v58, 0xffff, v15
	v_cndmask_b32_e32 v18, v18, v19, vcc
	v_bitop3_b32 v19, v20, s57, v20 bitop3:0xc
	v_or_b32_e32 v20, 0x8000, v20
	v_cmp_gt_i16_e32 vcc, 0, v47
	v_bitop3_b32 v42, v21, s57, v21 bitop3:0xc
	v_or_b32_e32 v21, 0x8000, v21
	v_cmp_gt_i16_e64 s[0:1], 0, v46
	v_bitop3_b32 v46, v22, s57, v22 bitop3:0xc
	v_or_b32_e32 v22, 0x8000, v22
	v_cmp_gt_i16_e64 s[6:7], 0, v45
	v_bitop3_b32 v45, v23, s57, v23 bitop3:0xc
	v_or_b32_e32 v23, 0x8000, v23
	v_cmp_gt_i16_e64 s[8:9], 0, v44
	v_bitop3_b32 v44, v48, s57, v48 bitop3:0xc
	v_or_b32_e32 v47, 0x8000, v48
	v_cmp_gt_i16_e64 s[10:11], 0, v43
	v_bitop3_b32 v43, v49, s57, v49 bitop3:0xc
	v_or_b32_e32 v48, 0x8000, v49
	v_cmp_gt_i16_e64 s[12:13], 0, v17
	v_bitop3_b32 v17, v50, s57, v50 bitop3:0xc
	v_or_b32_e32 v49, 0x8000, v50
	v_cmp_gt_i16_e64 s[14:15], 0, v16
	v_bitop3_b32 v16, v51, s57, v51 bitop3:0xc
	v_or_b32_e32 v50, 0x8000, v51
	v_cmp_gt_i16_e64 s[16:17], 0, v14
	v_bitop3_b32 v14, v52, s57, v52 bitop3:0xc
	v_or_b32_e32 v51, 0x8000, v52
	v_cmp_gt_i16_e64 s[18:19], 0, v13
	v_bitop3_b32 v13, v53, s57, v53 bitop3:0xc
	v_or_b32_e32 v52, 0x8000, v53
	v_cmp_gt_i16_e64 s[20:21], 0, v12
	v_bitop3_b32 v12, v54, s57, v54 bitop3:0xc
	v_or_b32_e32 v53, 0x8000, v54
	v_cmp_gt_i16_e64 s[24:25], 0, v11
	v_bitop3_b32 v11, v55, s57, v55 bitop3:0xc
	v_or_b32_e32 v54, 0x8000, v55
	v_cmp_gt_i16_e64 s[26:27], 0, v10
	v_bitop3_b32 v10, v56, s57, v56 bitop3:0xc
	v_or_b32_e32 v55, 0x8000, v56
	v_cmp_gt_i16_e64 s[28:29], 0, v9
	v_bitop3_b32 v9, v57, s57, v57 bitop3:0xc
	v_or_b32_e32 v56, 0x8000, v57
	v_cmp_gt_i16_e64 s[30:31], 0, v8
	v_bitop3_b32 v8, v58, s57, v58 bitop3:0xc
	v_or_b32_e32 v57, 0x8000, v58
	v_cmp_gt_i16_e64 s[34:35], 0, v15
	v_lshlrev_b32_e32 v15, 16, v18
	v_cndmask_b32_e32 v18, v20, v19, vcc
	v_cndmask_b32_e64 v19, v21, v42, s[0:1]
	v_cndmask_b32_e64 v20, v22, v46, s[6:7]
	v_cndmask_b32_e64 v21, v23, v45, s[8:9]
	v_cndmask_b32_e64 v22, v47, v44, s[10:11]
	v_cndmask_b32_e64 v23, v48, v43, s[12:13]
	v_cndmask_b32_e64 v17, v49, v17, s[14:15]
	v_cndmask_b32_e64 v16, v50, v16, s[16:17]
	v_cndmask_b32_e64 v14, v51, v14, s[18:19]
	v_cndmask_b32_e64 v13, v52, v13, s[20:21]
	v_cndmask_b32_e64 v12, v53, v12, s[24:25]
	v_cndmask_b32_e64 v11, v54, v11, s[26:27]
	v_cndmask_b32_e64 v10, v55, v10, s[28:29]
	v_cndmask_b32_e64 v9, v56, v9, s[30:31]
	v_cndmask_b32_e64 v8, v57, v8, s[34:35]
	v_lshlrev_b32_e32 v18, 16, v18
	v_lshlrev_b32_e32 v19, 16, v19
	v_lshlrev_b32_e32 v20, 16, v20
	v_lshlrev_b32_e32 v21, 16, v21
	v_lshlrev_b32_e32 v22, 16, v22
	v_lshlrev_b32_e32 v23, 16, v23
	v_lshlrev_b32_e32 v17, 16, v17
	v_lshlrev_b32_e32 v16, 16, v16
	v_lshlrev_b32_e32 v14, 16, v14
	v_lshlrev_b32_e32 v13, 16, v13
	v_lshlrev_b32_e32 v12, 16, v12
	v_lshlrev_b32_e32 v11, 16, v11
	v_lshlrev_b32_e32 v10, 16, v10
	v_lshlrev_b32_e32 v9, 16, v9
	v_add3_u32 v15, s91, v15, 15
	v_lshl_add_u32 v8, v8, 16, s91
	v_add3_u32 v18, s91, v18, 14
	v_add3_u32 v19, s91, v19, 13
	v_add3_u32 v20, s91, v20, 12
	v_add3_u32 v21, s91, v21, 11
	v_add3_u32 v22, s91, v22, 10
	v_add3_u32 v23, s91, v23, 9
	v_add3_u32 v17, s91, v17, 8
	v_add3_u32 v16, s91, v16, 7
	v_add3_u32 v14, s91, v14, 6
	v_add3_u32 v13, s91, v13, 5
	v_add3_u32 v12, s91, v12, 4
; DI void topk_half(const _Float16* __restrict__ sp, unsigned (&R)[16]) {
;     ...
;     SORT16(Gk)
;     MERGE16(R, Gk)
	v_add3_u32 v11, s91, v11, 3
	v_add3_u32 v10, s91, v10, 2
	v_add3_u32 v9, s91, v9, 1
	v_max_u32_e32 v42, v15, v18
	v_min_u32_e32 v15, v15, v18
	v_max_u32_e32 v18, v19, v20
	v_min_u32_e32 v19, v19, v20
	v_max_u32_e32 v20, v21, v22
	v_min_u32_e32 v21, v21, v22
	v_max_u32_e32 v22, v23, v17
	v_min_u32_e32 v17, v23, v17
	v_max_u32_e32 v23, v16, v14
	v_min_u32_e32 v14, v16, v14
	v_max_u32_e32 v16, v13, v12
	v_min_u32_e32 v12, v13, v12
	v_max_u32_e32 v13, v11, v10
	v_min_u32_e32 v10, v11, v10
	v_max_u32_e32 v11, v9, v8
	v_min_u32_e32 v8, v9, v8
	v_max_u32_e32 v9, v42, v18
	v_min_u32_e32 v18, v42, v18
	v_max_u32_e32 v42, v15, v19
	v_min_u32_e32 v15, v15, v19
	v_max_u32_e32 v19, v20, v22
	v_min_u32_e32 v20, v20, v22
	v_max_u32_e32 v22, v21, v17
	v_min_u32_e32 v17, v21, v17
	v_max_u32_e32 v21, v23, v16
	v_min_u32_e32 v16, v23, v16
	v_max_u32_e32 v23, v14, v12
	v_min_u32_e32 v12, v14, v12
	v_max_u32_e32 v14, v13, v11
	v_min_u32_e32 v11, v13, v11
	v_max_u32_e32 v13, v10, v8
	v_min_u32_e32 v8, v10, v8
	v_max_u32_e32 v10, v42, v18
	v_min_u32_e32 v18, v42, v18
	v_max_u32_e32 v42, v22, v20
	v_min_u32_e32 v20, v22, v20
	v_max_u32_e32 v22, v23, v16
	v_min_u32_e32 v16, v23, v16
	v_max_u32_e32 v23, v13, v11
	v_min_u32_e32 v11, v13, v11
	v_max_u32_e32 v13, v9, v19
	v_min_u32_e32 v9, v9, v19
	v_max_u32_e32 v19, v15, v17
	v_min_u32_e32 v15, v15, v17
	v_max_u32_e32 v17, v21, v14
	v_min_u32_e32 v14, v21, v14
	v_max_u32_e32 v21, v12, v8
	v_min_u32_e32 v8, v12, v8
	v_max_u32_e32 v12, v10, v42
	v_min_u32_e32 v10, v10, v42
	v_max_u32_e32 v42, v18, v20
	v_min_u32_e32 v18, v18, v20
	v_max_u32_e32 v20, v22, v23
	v_min_u32_e32 v22, v22, v23
	v_max_u32_e32 v23, v16, v11
	v_min_u32_e32 v11, v16, v11
	v_min_u32_e32 v16, v13, v17
	v_max_u32_e32 v43, v15, v8
	v_min_u32_e32 v8, v15, v8
	v_max3_u32 v13, v37, v13, v17
	v_max_u32_e32 v15, v42, v9
	v_min_u32_e32 v9, v42, v9
	v_max_u32_e32 v17, v19, v10
	v_min_u32_e32 v10, v19, v10
	v_max_u32_e32 v19, v23, v14
	v_min_u32_e32 v14, v23, v14
	v_max_u32_e32 v23, v21, v22
	v_min_u32_e32 v21, v21, v22
	v_max_u32_e32 v22, v12, v15
	v_min_u32_e32 v12, v12, v15
	v_max_u32_e32 v15, v17, v9
	v_min_u32_e32 v9, v17, v9
	v_max_u32_e32 v17, v10, v18
	v_min_u32_e32 v10, v10, v18
	v_max_u32_e32 v18, v20, v19
	v_min_u32_e32 v19, v20, v19
	v_max_u32_e32 v20, v23, v14
	v_min_u32_e32 v14, v23, v14
	v_max_u32_e32 v23, v21, v11
	v_min_u32_e32 v11, v21, v11
	v_max_u32_e32 v21, v22, v18
	v_min_u32_e32 v18, v22, v18
	v_max_u32_e32 v22, v12, v19
	v_min_u32_e32 v12, v12, v19
	v_max_u32_e32 v19, v15, v20
	v_min_u32_e32 v15, v15, v20
	v_max_u32_e32 v20, v9, v14
	v_min_u32_e32 v9, v9, v14
	v_max_u32_e32 v14, v17, v23
	v_min_u32_e32 v17, v17, v23
	v_max_u32_e32 v23, v10, v11
	v_min_u32_e32 v10, v10, v11
	v_max_u32_e32 v11, v20, v16
	v_min_u32_e32 v16, v20, v16
	v_max_u32_e32 v20, v14, v18
	v_min_u32_e32 v14, v14, v18
	v_max_u32_e32 v18, v23, v12
	v_min_u32_e32 v12, v23, v12
	v_max_u32_e32 v23, v43, v15
	v_min_u32_e32 v15, v43, v15
	v_max_u32_e32 v8, v35, v8
	v_max_u32_e32 v35, v22, v11
	v_min_u32_e32 v11, v22, v11
	v_max_u32_e32 v22, v19, v20
	v_min_u32_e32 v19, v19, v20
	v_max_u32_e32 v20, v18, v16
	v_min_u32_e32 v16, v18, v16
	v_max_u32_e32 v18, v23, v14
	v_min_u32_e32 v14, v23, v14
	v_max_u32_e32 v23, v12, v9
	v_min_u32_e32 v9, v12, v9
	v_max_u32_e32 v12, v15, v17
	v_min_u32_e32 v15, v15, v17
	v_min_u32_e32 v17, v21, v35
	v_min_u32_e32 v37, v22, v11
	v_min_u32_e32 v42, v19, v20
	v_min_u32_e32 v43, v18, v16
	v_min_u32_e32 v44, v14, v23
	v_min_u32_e32 v45, v12, v9
	v_min_u32_e32 v46, v15, v10
	v_max3_u32 v10, v40, v15, v10
	v_max3_u32 v9, v39, v12, v9
	v_max3_u32 v12, v38, v14, v23
	v_max3_u32 v14, v33, v18, v16
	v_max3_u32 v15, v31, v19, v20
	v_max3_u32 v3, v3, v22, v11
	v_max3_u32 v11, v34, v21, v35
	v_max_u32_e32 v16, v24, v46
	v_max_u32_e32 v18, v41, v45
	v_max_u32_e32 v19, v25, v44
	v_max_u32_e32 v20, v36, v43
	v_max_u32_e32 v21, v32, v42
	v_max_u32_e32 v22, v30, v37
	v_max_u32_e32 v1, v1, v17
	v_max_u32_e32 v17, v8, v14
	v_min_u32_e32 v8, v8, v14
	v_max_u32_e32 v14, v10, v15
	v_min_u32_e32 v10, v10, v15
	v_max_u32_e32 v15, v9, v3
	v_min_u32_e32 v3, v9, v3
	v_max_u32_e32 v9, v12, v11
	v_min_u32_e32 v11, v12, v11
	v_max_u32_e32 v12, v16, v21
	v_min_u32_e32 v16, v16, v21
	v_max_u32_e32 v21, v18, v22
	v_min_u32_e32 v18, v18, v22
	v_max_u32_e32 v22, v19, v1
	v_min_u32_e32 v1, v19, v1
	v_max_u32_e32 v19, v20, v13
	v_min_u32_e32 v13, v20, v13
	v_max_u32_e32 v20, v17, v15
	v_min_u32_e32 v15, v17, v15
	v_max_u32_e32 v17, v14, v9
	v_min_u32_e32 v9, v14, v9
	v_max_u32_e32 v14, v8, v3
	v_min_u32_e32 v3, v8, v3
	v_max_u32_e32 v8, v10, v11
	v_min_u32_e32 v10, v10, v11
	v_max_u32_e32 v11, v12, v22
	v_min_u32_e32 v12, v12, v22
	v_max_u32_e32 v22, v21, v19
	v_min_u32_e32 v19, v21, v19
	v_max_u32_e32 v21, v16, v1
	v_min_u32_e32 v1, v16, v1
	v_max_u32_e32 v16, v18, v13
	v_min_u32_e32 v13, v18, v13
	s_add_i32 s91, s91, -16
	v_max_u32_e32 v18, v20, v17
	v_min_u32_e32 v17, v20, v17
	v_max_u32_e32 v20, v15, v9
	v_min_u32_e32 v9, v15, v9
	v_max_u32_e32 v15, v14, v8
	v_min_u32_e32 v8, v14, v8
	v_max_u32_e32 v14, v3, v10
	v_min_u32_e32 v10, v3, v10
	v_max_u32_e32 v3, v11, v22
	v_min_u32_e32 v11, v11, v22
	v_max_u32_e32 v22, v12, v19
	v_min_u32_e32 v12, v12, v19
	v_max_u32_e32 v19, v21, v16
	v_min_u32_e32 v16, v21, v16
	v_max_u32_e32 v21, v1, v13
	v_min_u32_e32 v13, v1, v13
	s_cmp_lg_u32 s91, -16
	v_max_u32_e32 v35, v18, v3
	v_min_u32_e32 v24, v18, v3
	v_max_u32_e32 v40, v17, v11
	v_min_u32_e32 v41, v17, v11
	v_max_u32_e32 v39, v20, v22
	v_min_u32_e32 v25, v20, v22
	v_max_u32_e32 v38, v9, v12
	v_min_u32_e32 v36, v9, v12
	v_max_u32_e32 v33, v15, v19
	v_min_u32_e32 v32, v15, v19
	v_max_u32_e32 v31, v8, v16
	v_min_u32_e32 v30, v8, v16
	v_max_u32_e32 v3, v14, v21
	v_min_u32_e32 v1, v14, v21
	v_max_u32_e32 v34, v10, v13
	v_min_u32_e32 v37, v10, v13
	s_cbranch_scc1 .LBB0_1184
	v_lshl_add_u64 v[4:5], s[46:47], 0, v[4:5]
	v_mov_b32_e32 v55, 0
	s_movk_i32 s91, 0x70
	v_mov_b32_e32 v49, 0
	v_mov_b32_e32 v54, 0
	v_mov_b32_e32 v46, 0
	v_mov_b32_e32 v52, 0
	v_mov_b32_e32 v45, 0
	v_mov_b32_e32 v53, 0
	v_mov_b32_e32 v44, 0
	v_mov_b32_e32 v50, 0
	v_mov_b32_e32 v43, 0
	v_mov_b32_e32 v51, 0
	v_mov_b32_e32 v42, 0
	v_mov_b32_e32 v47, 0
	v_mov_b32_e32 v23, 0
	v_mov_b32_e32 v48, 0
	v_mov_b32_e32 v56, 0
; DI void topk_half(const _Float16* __restrict__ sp, unsigned (&R)[16]) {
; #pragma unroll
;   for (int e = 0; e < 16; ++e) R[e] = 0u;
; #pragma unroll 1
;   for (int gi = 0; gi < 8; ++gi) {
;     unsigned Gk[16];
; #pragma unroll
;     for (int e = 0; e < 16; ++e) {
;       const int n = gi * 16 + e;
;       const unsigned bits = __builtin_bit_cast(unsigned short, sp[(long)n * NTOK]);
;       const unsigned o = (bits & 0x8000u) ? (~bits & 0xffffu) : (bits | 0x8000u);
;       Gk[e] = (o << 16) | (unsigned)(127 - n);
;     }
.LBB0_1186:
	global_load_dwordx4 v[90:93], v86, s[40:41]
	v_add_u32_e32 v87, 0x80000, v86
	global_load_dwordx4 v[94:97], v87, s[40:41]
	v_add_u32_e32 v86, 0x100000, v86
	s_waitcnt vmcnt(0)
	ds_write_b128 v100, v[90:93]
	ds_write_b128 v100, v[94:97] offset:1024
	s_waitcnt lgkmcnt(0)
	ds_read_u16 v22, v101
	ds_read_u16 v61, v101 offset:128
	ds_read_u16 v60, v101 offset:256
	ds_read_u16 v59, v101 offset:384
	ds_read_u16 v58, v101 offset:512
	ds_read_u16 v57, v101 offset:640
	ds_read_u16 v15, v101 offset:768
	ds_read_u16 v14, v101 offset:896
	ds_read_u16 v12, v101 offset:1024
	ds_read_u16 v11, v101 offset:1152
	ds_read_u16 v10, v101 offset:1280
	ds_read_u16 v9, v101 offset:1408
	ds_read_u16 v8, v101 offset:1536
	ds_read_u16 v7, v101 offset:1664
	ds_read_u16 v6, v101 offset:1792
	ds_read_u16 v13, v101 offset:1920
	s_waitcnt lgkmcnt(0)
	v_and_b32_e32 v16, 0xffff, v22
	v_bitop3_b32 v17, v16, s57, v16 bitop3:0xc
	v_or_b32_e32 v16, 0x8000, v16
	v_cmp_gt_i16_e32 vcc, 0, v22
	v_and_b32_e32 v18, 0xffff, v61
	v_and_b32_e32 v19, 0xffff, v60
	v_and_b32_e32 v20, 0xffff, v59
	v_and_b32_e32 v21, 0xffff, v58
	v_and_b32_e32 v62, 0xffff, v57
	v_and_b32_e32 v63, 0xffff, v15
	v_and_b32_e32 v64, 0xffff, v14
	v_and_b32_e32 v65, 0xffff, v12
	v_and_b32_e32 v66, 0xffff, v11
	v_and_b32_e32 v67, 0xffff, v10
	v_and_b32_e32 v68, 0xffff, v9
	v_and_b32_e32 v69, 0xffff, v8
	v_and_b32_e32 v70, 0xffff, v7
	v_and_b32_e32 v71, 0xffff, v6
	v_and_b32_e32 v72, 0xffff, v13
	v_cndmask_b32_e32 v16, v16, v17, vcc
	v_bitop3_b32 v17, v18, s57, v18 bitop3:0xc
	v_or_b32_e32 v18, 0x8000, v18
	v_cmp_gt_i16_e32 vcc, 0, v61
	v_bitop3_b32 v22, v19, s57, v19 bitop3:0xc
	v_or_b32_e32 v19, 0x8000, v19
	v_cmp_gt_i16_e64 s[0:1], 0, v60
	v_bitop3_b32 v60, v20, s57, v20 bitop3:0xc
	v_or_b32_e32 v20, 0x8000, v20
	v_cmp_gt_i16_e64 s[6:7], 0, v59
	v_bitop3_b32 v59, v21, s57, v21 bitop3:0xc
	v_or_b32_e32 v21, 0x8000, v21
	v_cmp_gt_i16_e64 s[8:9], 0, v58
	v_bitop3_b32 v58, v62, s57, v62 bitop3:0xc
	v_or_b32_e32 v61, 0x8000, v62
	v_cmp_gt_i16_e64 s[10:11], 0, v57
	v_bitop3_b32 v57, v63, s57, v63 bitop3:0xc
	v_or_b32_e32 v62, 0x8000, v63
	v_cmp_gt_i16_e64 s[12:13], 0, v15
	v_bitop3_b32 v15, v64, s57, v64 bitop3:0xc
	v_or_b32_e32 v63, 0x8000, v64
	v_cmp_gt_i16_e64 s[14:15], 0, v14
	v_bitop3_b32 v14, v65, s57, v65 bitop3:0xc
	v_or_b32_e32 v64, 0x8000, v65
	v_cmp_gt_i16_e64 s[16:17], 0, v12
	v_bitop3_b32 v12, v66, s57, v66 bitop3:0xc
	v_or_b32_e32 v65, 0x8000, v66
	v_cmp_gt_i16_e64 s[18:19], 0, v11
	v_bitop3_b32 v11, v67, s57, v67 bitop3:0xc
	v_or_b32_e32 v66, 0x8000, v67
	v_cmp_gt_i16_e64 s[20:21], 0, v10
	v_bitop3_b32 v10, v68, s57, v68 bitop3:0xc
	v_or_b32_e32 v67, 0x8000, v68
	v_cmp_gt_i16_e64 s[24:25], 0, v9
	v_bitop3_b32 v9, v69, s57, v69 bitop3:0xc
	v_or_b32_e32 v68, 0x8000, v69
	v_cmp_gt_i16_e64 s[26:27], 0, v8
	v_bitop3_b32 v8, v70, s57, v70 bitop3:0xc
	v_or_b32_e32 v69, 0x8000, v70
	v_cmp_gt_i16_e64 s[28:29], 0, v7
	v_bitop3_b32 v7, v71, s57, v71 bitop3:0xc
	v_or_b32_e32 v70, 0x8000, v71
	v_cmp_gt_i16_e64 s[30:31], 0, v6
	v_bitop3_b32 v6, v72, s57, v72 bitop3:0xc
	v_or_b32_e32 v71, 0x8000, v72
	v_cmp_gt_i16_e64 s[34:35], 0, v13
	v_lshlrev_b32_e32 v13, 16, v16
	v_cndmask_b32_e32 v16, v18, v17, vcc
	v_cndmask_b32_e64 v17, v19, v22, s[0:1]
	v_cndmask_b32_e64 v18, v20, v60, s[6:7]
	v_cndmask_b32_e64 v19, v21, v59, s[8:9]
	v_cndmask_b32_e64 v20, v61, v58, s[10:11]
	v_cndmask_b32_e64 v21, v62, v57, s[12:13]
	v_cndmask_b32_e64 v15, v63, v15, s[14:15]
	v_cndmask_b32_e64 v14, v64, v14, s[16:17]
	v_cndmask_b32_e64 v12, v65, v12, s[18:19]
	v_cndmask_b32_e64 v11, v66, v11, s[20:21]
	v_cndmask_b32_e64 v10, v67, v10, s[24:25]
	v_cndmask_b32_e64 v9, v68, v9, s[26:27]
	v_cndmask_b32_e64 v8, v69, v8, s[28:29]
	v_cndmask_b32_e64 v7, v70, v7, s[30:31]
	v_cndmask_b32_e64 v6, v71, v6, s[34:35]
	v_lshlrev_b32_e32 v16, 16, v16
	v_lshlrev_b32_e32 v17, 16, v17
	v_lshlrev_b32_e32 v18, 16, v18
	v_lshlrev_b32_e32 v19, 16, v19
	v_lshlrev_b32_e32 v20, 16, v20
	v_lshlrev_b32_e32 v21, 16, v21
	v_lshlrev_b32_e32 v15, 16, v15
	v_lshlrev_b32_e32 v14, 16, v14
	v_lshlrev_b32_e32 v12, 16, v12
	v_lshlrev_b32_e32 v11, 16, v11
	v_lshlrev_b32_e32 v10, 16, v10
	v_lshlrev_b32_e32 v9, 16, v9
	v_lshlrev_b32_e32 v8, 16, v8
	v_lshlrev_b32_e32 v7, 16, v7
	v_add3_u32 v13, s91, v13, 15
	v_lshl_add_u32 v6, v6, 16, s91
	v_add3_u32 v16, s91, v16, 14
	v_add3_u32 v17, s91, v17, 13
	v_add3_u32 v18, s91, v18, 12
	v_add3_u32 v19, s91, v19, 11
	v_add3_u32 v20, s91, v20, 10
	v_add3_u32 v21, s91, v21, 9
	v_add3_u32 v15, s91, v15, 8
	v_add3_u32 v14, s91, v14, 7
	v_add3_u32 v12, s91, v12, 6
	v_add3_u32 v11, s91, v11, 5
	v_add3_u32 v10, s91, v10, 4
	v_add3_u32 v9, s91, v9, 3
	v_add3_u32 v8, s91, v8, 2
	v_add3_u32 v7, s91, v7, 1
	v_max_u32_e32 v22, v13, v16
	v_min_u32_e32 v13, v13, v16
	v_max_u32_e32 v16, v17, v18
	v_min_u32_e32 v17, v17, v18
	v_max_u32_e32 v18, v19, v20
	v_min_u32_e32 v19, v19, v20
	v_max_u32_e32 v20, v21, v15
	v_min_u32_e32 v15, v21, v15
	v_max_u32_e32 v21, v14, v12
	v_min_u32_e32 v12, v14, v12
	v_max_u32_e32 v14, v11, v10
	v_min_u32_e32 v10, v11, v10
	v_max_u32_e32 v11, v9, v8
	v_min_u32_e32 v8, v9, v8
	v_max_u32_e32 v9, v7, v6
	v_min_u32_e32 v6, v7, v6
	v_max_u32_e32 v7, v22, v16
	v_min_u32_e32 v16, v22, v16
	v_max_u32_e32 v22, v13, v17
	v_min_u32_e32 v13, v13, v17
	v_max_u32_e32 v17, v18, v20
	v_min_u32_e32 v18, v18, v20
	v_max_u32_e32 v20, v19, v15
	v_min_u32_e32 v15, v19, v15
	v_max_u32_e32 v19, v21, v14
	v_min_u32_e32 v14, v21, v14
	v_max_u32_e32 v21, v12, v10
	v_min_u32_e32 v10, v12, v10
	v_max_u32_e32 v12, v11, v9
	v_min_u32_e32 v9, v11, v9
	v_max_u32_e32 v11, v8, v6
	v_min_u32_e32 v6, v8, v6
	v_max_u32_e32 v8, v22, v16
; DI void topk_half(const _Float16* __restrict__ sp, unsigned (&R)[16]) {
;     ...
;     SORT16(Gk)
;     MERGE16(R, Gk)
	v_min_u32_e32 v16, v22, v16
	v_max_u32_e32 v22, v20, v18
	v_min_u32_e32 v18, v20, v18
	v_max_u32_e32 v20, v21, v14
	v_min_u32_e32 v14, v21, v14
	v_max_u32_e32 v21, v11, v9
	v_min_u32_e32 v9, v11, v9
	v_max_u32_e32 v11, v7, v17
	v_min_u32_e32 v7, v7, v17
	v_max_u32_e32 v17, v13, v15
	v_min_u32_e32 v13, v13, v15
	v_max_u32_e32 v15, v19, v12
	v_min_u32_e32 v12, v19, v12
	v_max_u32_e32 v19, v10, v6
	v_min_u32_e32 v6, v10, v6
	v_max_u32_e32 v10, v8, v22
	v_min_u32_e32 v8, v8, v22
	v_max_u32_e32 v22, v16, v18
	v_min_u32_e32 v16, v16, v18
	v_max_u32_e32 v18, v20, v21
	v_min_u32_e32 v20, v20, v21
	v_max_u32_e32 v21, v14, v9
	v_min_u32_e32 v9, v14, v9
	v_min_u32_e32 v14, v11, v15
	v_max_u32_e32 v57, v13, v6
	v_min_u32_e32 v6, v13, v6
	v_max3_u32 v11, v56, v11, v15
	v_max_u32_e32 v13, v22, v7
	v_min_u32_e32 v7, v22, v7
	v_max_u32_e32 v15, v17, v8
	v_min_u32_e32 v8, v17, v8
	v_max_u32_e32 v17, v21, v12
	v_min_u32_e32 v12, v21, v12
	v_max_u32_e32 v21, v19, v20
	v_min_u32_e32 v19, v19, v20
	v_max_u32_e32 v20, v10, v13
	v_min_u32_e32 v10, v10, v13
	v_max_u32_e32 v13, v15, v7
	v_min_u32_e32 v7, v15, v7
	v_max_u32_e32 v15, v8, v16
	v_min_u32_e32 v8, v8, v16
	v_max_u32_e32 v16, v18, v17
	v_min_u32_e32 v17, v18, v17
	v_max_u32_e32 v18, v21, v12
	v_min_u32_e32 v12, v21, v12
	v_max_u32_e32 v21, v19, v9
	v_min_u32_e32 v9, v19, v9
	v_max_u32_e32 v19, v20, v16
	v_min_u32_e32 v16, v20, v16
	v_max_u32_e32 v20, v10, v17
	v_min_u32_e32 v10, v10, v17
	v_max_u32_e32 v17, v13, v18
	v_min_u32_e32 v13, v13, v18
	v_max_u32_e32 v18, v7, v12
	v_min_u32_e32 v7, v7, v12
	v_max_u32_e32 v12, v15, v21
	v_min_u32_e32 v15, v15, v21
	v_max_u32_e32 v21, v8, v9
	v_min_u32_e32 v8, v8, v9
	v_max_u32_e32 v9, v18, v14
	v_min_u32_e32 v14, v18, v14
	v_max_u32_e32 v18, v12, v16
	v_min_u32_e32 v12, v12, v16
	v_max_u32_e32 v16, v21, v10
	v_min_u32_e32 v10, v21, v10
	v_max_u32_e32 v21, v57, v13
	v_min_u32_e32 v13, v57, v13
	v_max_u32_e32 v22, v20, v9
	v_min_u32_e32 v9, v20, v9
	v_max_u32_e32 v20, v17, v18
	v_min_u32_e32 v17, v17, v18
	v_max_u32_e32 v18, v16, v14
	v_min_u32_e32 v14, v16, v14
	v_max_u32_e32 v16, v21, v12
	v_min_u32_e32 v12, v21, v12
	v_max_u32_e32 v21, v10, v7
	v_min_u32_e32 v7, v10, v7
	v_max_u32_e32 v10, v13, v15
	v_min_u32_e32 v13, v13, v15
	v_max_u32_e32 v6, v55, v6
	v_min_u32_e32 v15, v19, v22
	v_min_u32_e32 v55, v20, v9
	v_min_u32_e32 v56, v17, v18
	v_min_u32_e32 v57, v16, v14
	v_min_u32_e32 v58, v12, v21
	v_min_u32_e32 v59, v10, v7
	v_min_u32_e32 v60, v13, v8
	v_max3_u32 v8, v54, v13, v8
	v_max3_u32 v7, v52, v10, v7
	v_max3_u32 v10, v53, v12, v21
	v_max3_u32 v12, v50, v16, v14
	v_max3_u32 v13, v51, v17, v18
	v_max3_u32 v9, v47, v20, v9
	v_max3_u32 v14, v48, v19, v22
	v_max_u32_e32 v16, v49, v60
	v_max_u32_e32 v17, v46, v59
	v_max_u32_e32 v18, v45, v58
	v_max_u32_e32 v19, v44, v57
	v_max_u32_e32 v20, v43, v56
	v_max_u32_e32 v21, v42, v55
	v_max_u32_e32 v15, v23, v15
	v_max_u32_e32 v22, v6, v12
	v_min_u32_e32 v6, v6, v12
	v_max_u32_e32 v12, v8, v13
	v_min_u32_e32 v8, v8, v13
	v_max_u32_e32 v13, v7, v9
	v_min_u32_e32 v7, v7, v9
	v_max_u32_e32 v9, v10, v14
	v_min_u32_e32 v10, v10, v14
	v_max_u32_e32 v14, v16, v20
	v_min_u32_e32 v16, v16, v20
	v_max_u32_e32 v20, v17, v21
	v_min_u32_e32 v17, v17, v21
	v_max_u32_e32 v21, v18, v15
	v_min_u32_e32 v15, v18, v15
	v_max_u32_e32 v18, v19, v11
	v_min_u32_e32 v11, v19, v11
	v_max_u32_e32 v19, v22, v13
	v_min_u32_e32 v13, v22, v13
	v_max_u32_e32 v22, v12, v9
	v_min_u32_e32 v9, v12, v9
	v_max_u32_e32 v12, v6, v7
	v_min_u32_e32 v6, v6, v7
	v_max_u32_e32 v7, v8, v10
	v_min_u32_e32 v8, v8, v10
	v_max_u32_e32 v10, v14, v21
	v_min_u32_e32 v14, v14, v21
	v_max_u32_e32 v21, v20, v18
	v_min_u32_e32 v18, v20, v18
	v_max_u32_e32 v20, v16, v15
	v_min_u32_e32 v15, v16, v15
	v_max_u32_e32 v16, v17, v11
	v_min_u32_e32 v11, v17, v11
	s_add_i32 s91, s91, -16
	v_max_u32_e32 v17, v19, v22
	v_min_u32_e32 v19, v19, v22
	v_max_u32_e32 v22, v13, v9
	v_min_u32_e32 v9, v13, v9
	v_max_u32_e32 v13, v12, v7
	v_min_u32_e32 v7, v12, v7
	v_max_u32_e32 v12, v6, v8
	v_min_u32_e32 v6, v6, v8
	v_max_u32_e32 v8, v10, v21
	v_min_u32_e32 v10, v10, v21
	v_max_u32_e32 v21, v14, v18
	v_min_u32_e32 v14, v14, v18
	v_max_u32_e32 v18, v20, v16
	v_min_u32_e32 v16, v20, v16
	v_max_u32_e32 v20, v15, v11
	v_min_u32_e32 v11, v15, v11
	s_cmp_lg_u32 s91, -16
	v_max_u32_e32 v55, v17, v8
	v_min_u32_e32 v49, v17, v8
	v_max_u32_e32 v54, v19, v10
	v_min_u32_e32 v46, v19, v10
	v_max_u32_e32 v52, v22, v21
	v_min_u32_e32 v45, v22, v21
	v_max_u32_e32 v53, v9, v14
	v_min_u32_e32 v44, v9, v14
	v_max_u32_e32 v50, v13, v18
	v_min_u32_e32 v43, v13, v18
	v_max_u32_e32 v51, v7, v16
	v_min_u32_e32 v42, v7, v16
	v_max_u32_e32 v47, v12, v20
	v_min_u32_e32 v23, v12, v20
	v_max_u32_e32 v48, v6, v11
	v_min_u32_e32 v56, v6, v11
	s_cbranch_scc1 .LBB0_1186
; DI float key_val16(unsigned k) { const unsigned o = k >> 16; const unsigned short b = (unsigned short)((o & 0x8000u) ? (o & 0x7fffu) : (~o & 0xffffu)); return (float)__builtin_bit_cast(_Float16, b); }
; DI void phase10(const Params& P, char* smem) {
;     ...
;     float v1[16], v2[16]; unsigned W1[4] = {0u, 0u, 0u, 0u}, W2[4] = {0u, 0u, 0u, 0u};
; #pragma unroll
;     for (int k = 0; k < 16; ++k) {
;       v1[k] = key_val16(R1[k]); v2[k] = key_val16(R2[k]);
;       W1[k >> 2] |= (127u - (R1[k] & 127u)) << ((k & 3) * 8);
;       W2[k >> 2] |= (127u - (R2[k] & 127u)) << ((k & 3) * 8);
;     }
	v_lshlrev_b32_e32 v5, 8, v24
	v_lshlrev_b32_e32 v6, 16, v40
	v_and_b32_e32 v4, 0x7f, v35
	v_and_b32_e32 v5, 0x7f00, v5
	v_and_b32_e32 v6, 0x7f0000, v6
	v_or3_b32 v4, v5, v4, v6
	v_and_b32_sdwa v5, v46, s57 dst_sel:DWORD dst_unused:UNUSED_PAD src0_sel:WORD_1 src1_sel:DWORD
	v_xor_b32_sdwa v7, v46, v27 dst_sel:DWORD dst_unused:UNUSED_PAD src0_sel:WORD_1 src1_sel:DWORD
	v_cmp_gt_i32_e32 vcc, 0, v46
	v_and_b32_sdwa v6, v41, s57 dst_sel:DWORD dst_unused:UNUSED_PAD src0_sel:WORD_1 src1_sel:DWORD
	v_xor_b32_sdwa v8, v41, v27 dst_sel:DWORD dst_unused:UNUSED_PAD src0_sel:WORD_1 src1_sel:DWORD
	v_cndmask_b32_e32 v5, v7, v5, vcc
	v_cmp_gt_i32_e32 vcc, 0, v41
	v_xor_b32_sdwa v7, v39, v27 dst_sel:DWORD dst_unused:UNUSED_PAD src0_sel:WORD_1 src1_sel:DWORD
	v_xor_b32_sdwa v11, v36, v27 dst_sel:DWORD dst_unused:UNUSED_PAD src0_sel:WORD_1 src1_sel:DWORD
	v_cndmask_b32_e32 v6, v8, v6, vcc
	v_cvt_f32_f16_e32 v8, v5
	v_lshlrev_b32_e32 v5, 24, v41
	v_and_b32_e32 v5, 0x7f000000, v5
	v_cvt_f32_f16_e32 v12, v6
	v_bitop3_b32 v15, v4, s75, v5 bitop3:0x36
	v_and_b32_sdwa v4, v54, s57 dst_sel:DWORD dst_unused:UNUSED_PAD src0_sel:WORD_1 src1_sel:DWORD
	v_xor_b32_sdwa v6, v54, v27 dst_sel:DWORD dst_unused:UNUSED_PAD src0_sel:WORD_1 src1_sel:DWORD
	v_cmp_gt_i32_e32 vcc, 0, v54
	v_and_b32_sdwa v5, v39, s57 dst_sel:DWORD dst_unused:UNUSED_PAD src0_sel:WORD_1 src1_sel:DWORD
	v_xor_b32_sdwa v13, v24, v27 dst_sel:DWORD dst_unused:UNUSED_PAD src0_sel:WORD_1 src1_sel:DWORD
	v_cndmask_b32_e32 v4, v6, v4, vcc
	v_cmp_gt_i32_e32 vcc, 0, v39
	v_cvt_f32_f16_e32 v9, v4
	v_and_b32_sdwa v4, v52, s57 dst_sel:DWORD dst_unused:UNUSED_PAD src0_sel:WORD_1 src1_sel:DWORD
	v_cndmask_b32_e32 v5, v7, v5, vcc
	v_xor_b32_sdwa v6, v52, v27 dst_sel:DWORD dst_unused:UNUSED_PAD src0_sel:WORD_1 src1_sel:DWORD
	v_cmp_gt_i32_e32 vcc, 0, v52
	v_cvt_f32_f16_e32 v10, v5
	v_and_b32_sdwa v5, v40, s57 dst_sel:DWORD dst_unused:UNUSED_PAD src0_sel:WORD_1 src1_sel:DWORD
	v_xor_b32_sdwa v7, v40, v27 dst_sel:DWORD dst_unused:UNUSED_PAD src0_sel:WORD_1 src1_sel:DWORD
	v_cndmask_b32_e32 v4, v6, v4, vcc
	v_cmp_gt_i32_e32 vcc, 0, v40
	v_not_b32_sdwa v6, v25 dst_sel:DWORD dst_unused:UNUSED_PAD src0_sel:WORD_1
	v_cvt_f32_f16_e32 v21, v4
	v_cndmask_b32_e32 v5, v7, v5, vcc
	v_cvt_f32_f16_e32 v22, v5
	v_bfe_u32 v5, v25, 16, 15
	v_cmp_gt_i32_e32 vcc, 0, v25
	v_not_b32_sdwa v7, v38 dst_sel:DWORD dst_unused:UNUSED_PAD src0_sel:WORD_1
	v_and_b32_e32 v4, 0x7f, v39
	v_cndmask_b32_e32 v5, v6, v5, vcc
	v_cvt_f32_f16_e32 v14, v5
	v_bfe_u32 v5, v45, 16, 15
	v_not_b32_sdwa v6, v45 dst_sel:DWORD dst_unused:UNUSED_PAD src0_sel:WORD_1
	v_cmp_gt_i32_e32 vcc, 0, v45
	s_movk_i32 s0, 0xfe
	v_xor_b32_sdwa v57, v50, v27 dst_sel:DWORD dst_unused:UNUSED_PAD src0_sel:WORD_1 src1_sel:DWORD
	v_cndmask_b32_e32 v5, v6, v5, vcc
	v_bfe_u32 v6, v38, 16, 15
	v_cmp_gt_i32_e32 vcc, 0, v38
	v_cvt_f32_f16_e32 v20, v5
	v_lshlrev_b32_e32 v5, 8, v25
	v_cndmask_b32_e32 v6, v7, v6, vcc
	v_cvt_f32_f16_e32 v16, v6
	v_bfe_u32 v6, v53, 16, 15
	v_not_b32_sdwa v7, v53 dst_sel:DWORD dst_unused:UNUSED_PAD src0_sel:WORD_1
	v_cmp_gt_i32_e32 vcc, 0, v53
	v_and_b32_e32 v5, 0x7f00, v5
	v_xor_b32_sdwa v81, v32, v27 dst_sel:DWORD dst_unused:UNUSED_PAD src0_sel:WORD_1 src1_sel:DWORD
	v_cndmask_b32_e32 v6, v7, v6, vcc
	v_cvt_f32_f16_e32 v25, v6
	v_lshlrev_b32_e32 v6, 16, v38
	v_and_b32_e32 v6, 0x7f0000, v6
	v_or3_b32 v4, v5, v4, v6
	v_and_b32_sdwa v5, v49, s57 dst_sel:DWORD dst_unused:UNUSED_PAD src0_sel:WORD_1 src1_sel:DWORD
	v_xor_b32_sdwa v7, v49, v27 dst_sel:DWORD dst_unused:UNUSED_PAD src0_sel:WORD_1 src1_sel:DWORD
	v_cmp_gt_i32_e32 vcc, 0, v49
	v_and_b32_sdwa v6, v36, s57 dst_sel:DWORD dst_unused:UNUSED_PAD src0_sel:WORD_1 src1_sel:DWORD
	v_xor_b32_sdwa v38, v35, v27 dst_sel:DWORD dst_unused:UNUSED_PAD src0_sel:WORD_1 src1_sel:DWORD
	v_cndmask_b32_e32 v5, v7, v5, vcc
	v_cmp_gt_i32_e32 vcc, 0, v36
	s_nop 1
	v_cndmask_b32_e32 v7, v11, v6, vcc
	v_cvt_f32_f16_e32 v18, v7
	v_and_b32_sdwa v7, v24, s57 dst_sel:DWORD dst_unused:UNUSED_PAD src0_sel:WORD_1 src1_sel:DWORD
	v_cmp_gt_i32_e32 vcc, 0, v24
	v_cvt_f32_f16_e32 v6, v5
	v_and_b32_sdwa v5, v44, s57 dst_sel:DWORD dst_unused:UNUSED_PAD src0_sel:WORD_1 src1_sel:DWORD
	v_xor_b32_sdwa v11, v44, v27 dst_sel:DWORD dst_unused:UNUSED_PAD src0_sel:WORD_1 src1_sel:DWORD
	v_cndmask_b32_e32 v7, v13, v7, vcc
	v_cmp_gt_i32_e32 vcc, 0, v44
	v_cvt_f32_f16_e32 v64, v7
	v_lshlrev_b32_e32 v7, 16, v31
	v_cndmask_b32_e32 v5, v11, v5, vcc
	v_cvt_f32_f16_e32 v24, v5
	v_lshlrev_b32_e32 v5, 24, v36
	v_and_b32_e32 v5, 0x7f000000, v5
	v_bitop3_b32 v17, v4, s75, v5 bitop3:0x36
	v_lshlrev_b32_e32 v5, 8, v32
	v_and_b32_e32 v4, 0x7f, v33
	v_and_b32_e32 v5, 0x7f00, v5
	v_and_b32_e32 v7, 0x7f0000, v7
	v_or3_b32 v4, v5, v4, v7
	v_lshlrev_b32_e32 v5, 24, v30
	v_and_b32_e32 v5, 0x7f000000, v5
	v_bitop3_b32 v19, v4, s75, v5 bitop3:0x36
	v_lshlrev_b32_e32 v5, 8, v1
	v_and_b32_e32 v11, 0x7f00, v5
	v_and_b32_sdwa v5, v55, s57 dst_sel:DWORD dst_unused:UNUSED_PAD src0_sel:WORD_1 src1_sel:DWORD
	v_xor_b32_sdwa v13, v55, v27 dst_sel:DWORD dst_unused:UNUSED_PAD src0_sel:WORD_1 src1_sel:DWORD
	v_cmp_gt_i32_e32 vcc, 0, v55
	v_and_b32_sdwa v7, v34, s57 dst_sel:DWORD dst_unused:UNUSED_PAD src0_sel:WORD_1 src1_sel:DWORD
	v_xor_b32_sdwa v36, v34, v27 dst_sel:DWORD dst_unused:UNUSED_PAD src0_sel:WORD_1 src1_sel:DWORD
	v_cndmask_b32_e32 v5, v13, v5, vcc
	v_cmp_gt_i32_e32 vcc, 0, v34
	v_and_b32_e32 v4, 0x7f, v3
	s_nop 0
	v_cndmask_b32_e32 v13, v36, v7, vcc
	v_cvt_f32_f16_e32 v7, v5
	v_cvt_f32_f16_e32 v5, v13
	v_bfe_u32 v13, v48, 16, 15
	v_not_b32_sdwa v36, v48 dst_sel:DWORD dst_unused:UNUSED_PAD src0_sel:WORD_1
	v_cmp_gt_i32_e32 vcc, 0, v48
	s_nop 1
	v_cndmask_b32_e32 v13, v36, v13, vcc
; DI float key_val16(unsigned k) { const unsigned o = k >> 16; const unsigned short b = (unsigned short)((o & 0x8000u) ? (o & 0x7fffu) : (~o & 0xffffu)); return (float)__builtin_bit_cast(_Float16, b); }
; DI unsigned candkey(float s, int pos) { const unsigned b = __float_as_uint(s); const unsigned o = (b >> 31) ? ~b : (b ^ 0x80000000u); return (o & 0xffffff00u) | (unsigned)(255 - pos); }
; DI void phase10(const Params& P, char* smem) {
;     ...
;     C0[0] = candkey(v1[0] + v2[0], 0);
;     C0[1] = candkey(v1[0] + v2[1], 1);
;     C0[2] = candkey(v1[0] + v2[2], 2);
;     C0[3] = candkey(v1[0] + v2[3], 3);
;     C0[4] = candkey(v1[0] + v2[4], 4);
;     C0[5] = candkey(v1[0] + v2[5], 5);
;     C0[6] = candkey(v1[0] + v2[6], 6);
;     C0[7] = candkey(v1[0] + v2[7], 7);
;     C0[8] = candkey(v1[0] + v2[8], 8);
;     C0[9] = candkey(v1[0] + v2[9], 9);
;     C0[10] = candkey(v1[0] + v2[10], 10);
;     C0[11] = candkey(v1[0] + v2[11], 11);
;     C0[12] = candkey(v1[0] + v2[12], 12);
;     C0[13] = candkey(v1[0] + v2[13], 13);
;     C0[14] = candkey(v1[0] + v2[14], 14);
;     C0[15] = candkey(v1[0] + v2[15], 15);
	v_cvt_f32_f16_e32 v67, v13
	v_lshlrev_b32_e32 v13, 16, v34
	v_and_b32_e32 v13, 0x7f0000, v13
	v_or3_b32 v11, v11, v4, v13
	v_bfe_u32 v4, v37, 16, 15
	v_not_b32_sdwa v13, v37 dst_sel:DWORD dst_unused:UNUSED_PAD src0_sel:WORD_1
	v_cmp_gt_i32_e32 vcc, 0, v37
	v_xor_b32_sdwa v36, v56, v27 dst_sel:DWORD dst_unused:UNUSED_PAD src0_sel:WORD_1 src1_sel:DWORD
	v_and_b32_sdwa v34, v35, s57 dst_sel:DWORD dst_unused:UNUSED_PAD src0_sel:WORD_1 src1_sel:DWORD
	v_cndmask_b32_e32 v4, v13, v4, vcc
	v_and_b32_sdwa v13, v56, s57 dst_sel:DWORD dst_unused:UNUSED_PAD src0_sel:WORD_1 src1_sel:DWORD
	v_cmp_gt_i32_e32 vcc, 0, v56
	v_cvt_f32_f16_e32 v4, v4
	s_nop 0
	v_cndmask_b32_e32 v13, v36, v13, vcc
	v_cmp_gt_i32_e32 vcc, 0, v35
	v_cvt_f32_f16_e32 v66, v13
	v_lshlrev_b32_e32 v13, 24, v37
	v_cndmask_b32_e32 v34, v38, v34, vcc
	v_cvt_f32_f16_e32 v68, v34
	v_and_b32_e32 v13, 0x7f000000, v13
	v_bitop3_b32 v34, v11, s75, v13 bitop3:0x36
	v_pk_add_f32 v[36:37], v[68:69], v[6:7] op_sel_hi:[0,1]
	v_cmp_lt_i32_e32 vcc, -1, v37
	v_pk_add_f32 v[38:39], v[68:69], v[8:9] op_sel_hi:[0,1]
	v_and_b32_e32 v13, 0xffffff00, v36
	v_cndmask_b32_e32 v11, v28, v29, vcc
	v_cmp_lt_i32_e32 vcc, -1, v36
	v_bitop3_b32 v35, v11, s3, v37 bitop3:0xde
	v_pk_add_f32 v[40:41], v[68:69], v[20:21] op_sel_hi:[0,1]
	v_cndmask_b32_e32 v11, v28, v29, vcc
	v_cmp_lt_i32_e32 vcc, -1, v39
	v_bitop3_b32 v36, v11, s0, v13 bitop3:0xde
	v_and_b32_e32 v13, 0xffffff00, v39
	v_cndmask_b32_e32 v11, v28, v29, vcc
	s_movk_i32 s0, 0xfd
	v_cmp_lt_i32_e32 vcc, -1, v38
	v_bitop3_b32 v37, v11, s0, v13 bitop3:0xde
	v_and_b32_e32 v13, 0xffffff00, v38
	v_cndmask_b32_e32 v11, v28, v29, vcc
	s_movk_i32 s0, 0xfc
	v_cmp_lt_i32_e32 vcc, -1, v41
	v_bitop3_b32 v38, v11, s0, v13 bitop3:0xde
	v_and_b32_e32 v13, 0xffffff00, v41
	v_cndmask_b32_e32 v11, v28, v29, vcc
	s_movk_i32 s0, 0xfb
	v_cmp_lt_i32_e32 vcc, -1, v40
	v_pk_add_f32 v[58:59], v[68:69], v[24:25] op_sel_hi:[0,1]
	v_bitop3_b32 v39, v11, s0, v13 bitop3:0xde
	v_cndmask_b32_e32 v11, v28, v29, vcc
	v_and_b32_e32 v13, 0xffffff00, v40
	s_movk_i32 s0, 0xfa
	v_cmp_lt_i32_e32 vcc, -1, v59
	v_bitop3_b32 v40, v11, s0, v13 bitop3:0xde
	v_and_b32_e32 v13, 0xffffff00, v59
	v_cndmask_b32_e32 v11, v28, v29, vcc
	s_movk_i32 s0, 0xf9
	v_bitop3_b32 v41, v11, s0, v13 bitop3:0xde
	v_and_b32_sdwa v11, v50, s57 dst_sel:DWORD dst_unused:UNUSED_PAD src0_sel:WORD_1 src1_sel:DWORD
	v_cmp_gt_i32_e32 vcc, 0, v50
	v_and_b32_sdwa v13, v43, s57 dst_sel:DWORD dst_unused:UNUSED_PAD src0_sel:WORD_1 src1_sel:DWORD
	v_xor_b32_sdwa v59, v43, v27 dst_sel:DWORD dst_unused:UNUSED_PAD src0_sel:WORD_1 src1_sel:DWORD
	v_cndmask_b32_e32 v11, v57, v11, vcc
	v_cmp_gt_i32_e32 vcc, 0, v43
	v_cvt_f32_f16_e32 v61, v11
	s_movk_i32 s0, 0xf8
	v_cndmask_b32_e32 v13, v59, v13, vcc
	v_cvt_f32_f16_e32 v60, v13
	v_cmp_lt_i32_e32 vcc, -1, v58
	v_and_b32_e32 v13, 0xffffff00, v58
	v_xor_b32_sdwa v59, v51, v27 dst_sel:DWORD dst_unused:UNUSED_PAD src0_sel:WORD_1 src1_sel:DWORD
	v_pk_add_f32 v[60:61], v[68:69], v[60:61] op_sel_hi:[0,1]
	v_cndmask_b32_e32 v11, v28, v29, vcc
	v_cmp_lt_i32_e32 vcc, -1, v61
	v_bitop3_b32 v57, v11, s0, v13 bitop3:0xde
	v_and_b32_e32 v13, 0xffffff00, v61
	v_cndmask_b32_e32 v11, v28, v29, vcc
	s_movk_i32 s0, 0xf7
	v_bitop3_b32 v58, v11, s0, v13 bitop3:0xde
	v_and_b32_sdwa v11, v51, s57 dst_sel:DWORD dst_unused:UNUSED_PAD src0_sel:WORD_1 src1_sel:DWORD
	v_cmp_gt_i32_e32 vcc, 0, v51
	v_and_b32_sdwa v13, v42, s57 dst_sel:DWORD dst_unused:UNUSED_PAD src0_sel:WORD_1 src1_sel:DWORD
	v_xor_b32_sdwa v61, v42, v27 dst_sel:DWORD dst_unused:UNUSED_PAD src0_sel:WORD_1 src1_sel:DWORD
	v_cndmask_b32_e32 v11, v59, v11, vcc
	v_cmp_gt_i32_e32 vcc, 0, v42
	v_cvt_f32_f16_e32 v63, v11
	s_movk_i32 s0, 0xf6
	v_cndmask_b32_e32 v13, v61, v13, vcc
	v_cvt_f32_f16_e32 v62, v13
	v_cmp_lt_i32_e32 vcc, -1, v60
	v_and_b32_e32 v13, 0xffffff00, v60
	v_xor_b32_sdwa v61, v47, v27 dst_sel:DWORD dst_unused:UNUSED_PAD src0_sel:WORD_1 src1_sel:DWORD
	v_pk_add_f32 v[62:63], v[68:69], v[62:63] op_sel_hi:[0,1]
	v_cndmask_b32_e32 v11, v28, v29, vcc
	v_cmp_lt_i32_e32 vcc, -1, v63
	v_bitop3_b32 v59, v11, s0, v13 bitop3:0xde
	v_and_b32_e32 v13, 0xffffff00, v63
	v_cndmask_b32_e32 v11, v28, v29, vcc
	s_movk_i32 s0, 0xf5
	v_bitop3_b32 v60, v11, s0, v13 bitop3:0xde
	v_and_b32_sdwa v11, v47, s57 dst_sel:DWORD dst_unused:UNUSED_PAD src0_sel:WORD_1 src1_sel:DWORD
	v_cmp_gt_i32_e32 vcc, 0, v47
	v_and_b32_sdwa v13, v23, s57 dst_sel:DWORD dst_unused:UNUSED_PAD src0_sel:WORD_1 src1_sel:DWORD
	v_xor_b32_sdwa v63, v23, v27 dst_sel:DWORD dst_unused:UNUSED_PAD src0_sel:WORD_1 src1_sel:DWORD
	v_cndmask_b32_e32 v11, v61, v11, vcc
	v_cmp_gt_i32_e32 vcc, 0, v23
	v_cvt_f32_f16_e32 v71, v11
	s_movk_i32 s0, 0xf4
	v_cndmask_b32_e32 v13, v63, v13, vcc
	v_cvt_f32_f16_e32 v70, v13
	v_cmp_lt_i32_e32 vcc, -1, v62
	v_and_b32_e32 v13, 0xffffff00, v62
	v_pk_add_f32 v[66:67], v[68:69], v[66:67] op_sel_hi:[0,1]
	v_pk_add_f32 v[70:71], v[68:69], v[70:71] op_sel_hi:[0,1]
	v_cndmask_b32_e32 v11, v28, v29, vcc
	v_cmp_lt_i32_e32 vcc, -1, v71
	v_bitop3_b32 v61, v11, s0, v13 bitop3:0xde
	v_and_b32_e32 v13, 0xffffff00, v71
	v_cndmask_b32_e32 v11, v28, v29, vcc
	s_movk_i32 s0, 0xf3
	v_cmp_lt_i32_e32 vcc, -1, v70
	v_bitop3_b32 v62, v11, s0, v13 bitop3:0xde
	v_and_b32_e32 v13, 0xffffff00, v70
	v_cndmask_b32_e32 v11, v28, v29, vcc
	s_movk_i32 s0, 0xf2
	v_cmp_lt_i32_e32 vcc, -1, v67
	v_bitop3_b32 v63, v11, s0, v13 bitop3:0xde
	v_and_b32_e32 v13, 0xffffff00, v67
	v_cndmask_b32_e32 v11, v28, v29, vcc
	s_movk_i32 s0, 0xf1
	v_bitop3_b32 v65, v11, s0, v13 bitop3:0xde
	v_cmp_lt_i32_e32 vcc, -1, v66
	v_and_b32_e32 v13, 0xffffff00, v66
	v_pk_add_f32 v[66:67], v[64:65], v[6:7] op_sel_hi:[0,1]
; DI unsigned candkey(float s, int pos) { const unsigned b = __float_as_uint(s); const unsigned o = (b >> 31) ? ~b : (b ^ 0x80000000u); return (o & 0xffffff00u) | (unsigned)(255 - pos); }
; DI void phase10(const Params& P, char* smem) {
;     ...
;     C0[0] = candkey(v1[0] + v2[0], 0);
;     C0[1] = candkey(v1[0] + v2[1], 1);
;     C0[2] = candkey(v1[0] + v2[2], 2);
;     C0[3] = candkey(v1[0] + v2[3], 3);
;     C0[4] = candkey(v1[0] + v2[4], 4);
;     C0[5] = candkey(v1[0] + v2[5], 5);
;     C0[6] = candkey(v1[0] + v2[6], 6);
;     C0[7] = candkey(v1[0] + v2[7], 7);
;     C0[8] = candkey(v1[0] + v2[8], 8);
;     C0[9] = candkey(v1[0] + v2[9], 9);
;     C0[10] = candkey(v1[0] + v2[10], 10);
;     C0[11] = candkey(v1[0] + v2[11], 11);
;     C0[12] = candkey(v1[0] + v2[12], 12);
;     C0[13] = candkey(v1[0] + v2[13], 13);
;     C0[14] = candkey(v1[0] + v2[14], 14);
;     C0[15] = candkey(v1[0] + v2[15], 15);
;     C1[0] = candkey(v1[1] + v2[0], 16);
;     C1[1] = candkey(v1[1] + v2[1], 17);
;     C1[2] = candkey(v1[1] + v2[2], 18);
;     C1[3] = candkey(v1[1] + v2[3], 19);
;     C1[4] = candkey(v1[1] + v2[4], 20);
;     C1[5] = candkey(v1[1] + v2[5], 21);
;     C1[6] = candkey(v1[1] + v2[6], 22);
;     C1[7] = candkey(v1[1] + v2[7], 23);
;     C1[8] = candkey(v1[2] + v2[0], 32);
;     C1[9] = candkey(v1[2] + v2[1], 33);
;     C1[10] = candkey(v1[2] + v2[2], 34);
;     C1[11] = candkey(v1[2] + v2[3], 35);
;     C1[12] = candkey(v1[2] + v2[4], 36);
;     C1[13] = candkey(v1[3] + v2[0], 48);
;     C1[14] = candkey(v1[3] + v2[1], 49);
;     C1[15] = candkey(v1[3] + v2[2], 50);
;     C2[0] = candkey(v1[3] + v2[3], 51);
;     C2[1] = candkey(v1[4] + v2[0], 64);
;     C2[2] = candkey(v1[4] + v2[1], 65);
;     C2[3] = candkey(v1[4] + v2[2], 66);
;     C2[4] = candkey(v1[5] + v2[0], 80);
;     C2[5] = candkey(v1[5] + v2[1], 81);
;     C2[6] = candkey(v1[6] + v2[0], 96);
;     C2[7] = candkey(v1[6] + v2[1], 97);
;     C2[8] = candkey(v1[7] + v2[0], 112);
;     C2[9] = candkey(v1[7] + v2[1], 113);
;     C2[10] = candkey(v1[8] + v2[0], 128);
;     C2[11] = candkey(v1[9] + v2[0], 144);
;     C2[12] = candkey(v1[10] + v2[0], 160);
;     C2[13] = candkey(v1[11] + v2[0], 176);
;     C2[14] = candkey(v1[12] + v2[0], 192);
;     C2[15] = candkey(v1[13] + v2[0], 208);
;     C3[0] = candkey(v1[14] + v2[0], 224);
;     C3[1] = candkey(v1[15] + v2[0], 240);
	v_cndmask_b32_e32 v11, v28, v29, vcc
	s_movk_i32 s0, 0xf0
	v_cmp_lt_i32_e32 vcc, -1, v67
	v_bitop3_b32 v68, v11, s0, v13 bitop3:0xde
	v_and_b32_e32 v13, 0xffffff00, v67
	v_cndmask_b32_e32 v11, v28, v29, vcc
	s_movk_i32 s0, 0xef
	v_bitop3_b32 v69, v11, s0, v13 bitop3:0xde
	v_cmp_lt_i32_e32 vcc, -1, v66
	v_and_b32_e32 v13, 0xffffff00, v66
	v_pk_add_f32 v[66:67], v[64:65], v[8:9] op_sel_hi:[0,1]
	v_cndmask_b32_e32 v11, v28, v29, vcc
	s_movk_i32 s0, 0xee
	v_cmp_lt_i32_e32 vcc, -1, v67
	v_bitop3_b32 v70, v11, s0, v13 bitop3:0xde
	v_and_b32_e32 v13, 0xffffff00, v67
	v_cndmask_b32_e32 v11, v28, v29, vcc
	s_movk_i32 s0, 0xed
	v_bitop3_b32 v71, v11, s0, v13 bitop3:0xde
	v_cmp_lt_i32_e32 vcc, -1, v66
	v_and_b32_e32 v13, 0xffffff00, v66
	v_pk_add_f32 v[66:67], v[64:65], v[20:21] op_sel_hi:[0,1]
	v_cndmask_b32_e32 v11, v28, v29, vcc
	s_movk_i32 s0, 0xec
	v_cmp_lt_i32_e32 vcc, -1, v67
	v_bitop3_b32 v72, v11, s0, v13 bitop3:0xde
	v_and_b32_e32 v13, 0xffffff00, v67
	v_cndmask_b32_e32 v11, v28, v29, vcc
	s_movk_i32 s0, 0xeb
	v_cmp_lt_i32_e32 vcc, -1, v66
	v_pk_add_f32 v[24:25], v[64:65], v[24:25] op_sel_hi:[0,1]
	v_bitop3_b32 v67, v11, s0, v13 bitop3:0xde
	v_cndmask_b32_e32 v11, v28, v29, vcc
	v_and_b32_e32 v13, 0xffffff00, v66
	s_movk_i32 s0, 0xea
	v_cmp_lt_i32_e32 vcc, -1, v25
	v_bitop3_b32 v66, v11, s0, v13 bitop3:0xde
	v_and_b32_e32 v13, 0xffffff00, v25
	v_cndmask_b32_e32 v11, v28, v29, vcc
	s_movk_i32 s0, 0xe9
	v_bitop3_b32 v64, v11, s0, v13 bitop3:0xde
	v_cmp_lt_i32_e32 vcc, -1, v24
	v_and_b32_e32 v13, 0xffffff00, v24
	v_pk_add_f32 v[24:25], v[22:23], v[6:7] op_sel_hi:[0,1]
	v_cndmask_b32_e32 v11, v28, v29, vcc
	v_cmp_lt_i32_e32 vcc, -1, v25
	v_bitop3_b32 v73, v11, s92, v13 bitop3:0xde
	v_and_b32_e32 v13, 0xffffff00, v25
	v_cndmask_b32_e32 v11, v28, v29, vcc
	v_bitop3_b32 v74, v11, s93, v13 bitop3:0xde
	v_cmp_lt_i32_e32 vcc, -1, v24
	v_and_b32_e32 v13, 0xffffff00, v24
	v_pk_add_f32 v[24:25], v[22:23], v[8:9] op_sel_hi:[0,1]
	v_cndmask_b32_e32 v11, v28, v29, vcc
	v_cmp_lt_i32_e32 vcc, -1, v25
	v_bitop3_b32 v75, v11, s94, v13 bitop3:0xde
	v_and_b32_e32 v13, 0xffffff00, v25
	v_cndmask_b32_e32 v11, v28, v29, vcc
	v_cmp_lt_i32_e32 vcc, -1, v24
	v_bitop3_b32 v76, v11, s95, v13 bitop3:0xde
	v_and_b32_e32 v13, 0xffffff00, v24
	v_cndmask_b32_e32 v11, v28, v29, vcc
	v_bitop3_b32 v77, v11, s96, v13 bitop3:0xde
	v_mov_b32_e32 v13, v22
	v_mov_b32_e32 v20, v7
	v_pk_add_f32 v[20:21], v[12:13], v[20:21]
	s_movk_i32 s0, 0x7f
	v_cmp_lt_i32_e32 vcc, -1, v21
	v_and_b32_e32 v13, 0xffffff00, v21
	v_mov_b32_e32 v21, v6
	v_cndmask_b32_e32 v11, v28, v29, vcc
	v_bitop3_b32 v22, v11, s97, v13 bitop3:0xde
	v_cmp_lt_i32_e32 vcc, -1, v20
	v_and_b32_e32 v13, 0xffffff00, v20
	v_mov_b32_e32 v20, v9
	v_pk_add_f32 v[24:25], v[12:13], v[20:21] op_sel_hi:[0,1]
	v_cndmask_b32_e32 v11, v28, v29, vcc
	v_cmp_lt_i32_e32 vcc, -1, v25
	v_bitop3_b32 v78, v11, s4, v13 bitop3:0xde
	v_and_b32_e32 v11, 0xffffff00, v25
	v_cndmask_b32_e32 v9, v28, v29, vcc
	v_cmp_lt_i32_e32 vcc, -1, v24
	v_bitop3_b32 v25, v9, s5, v11 bitop3:0xde
	v_and_b32_e32 v11, 0xffffff00, v24
	v_cndmask_b32_e32 v9, v28, v29, vcc
	v_bitop3_b32 v24, v9, s80, v11 bitop3:0xde
	v_mov_b32_e32 v11, v12
	v_mov_b32_e32 v12, v7
	v_mov_b32_e32 v13, v8
	v_pk_add_f32 v[8:9], v[10:11], v[12:13]
	s_nop 0
	v_cmp_lt_i32_e32 vcc, -1, v9
	v_and_b32_e32 v9, 0xffffff00, v9
	s_nop 0
	v_cndmask_b32_e32 v11, v28, v29, vcc
	v_cmp_lt_i32_e32 vcc, -1, v8
	v_bitop3_b32 v12, v11, s81, v9 bitop3:0xde
	v_and_b32_e32 v8, 0xffffff00, v8
	v_cndmask_b32_e32 v9, v28, v29, vcc
	v_bitop3_b32 v13, v9, s22, v8 bitop3:0xde
	v_pk_add_f32 v[8:9], v[10:11], v[20:21] op_sel_hi:[0,1]
	v_cmp_lt_i32_e32 vcc, -1, v9
	v_and_b32_e32 v9, 0xffffff00, v9
	v_xor_b32_sdwa v11, v33, v27 dst_sel:DWORD dst_unused:UNUSED_PAD src0_sel:WORD_1 src1_sel:DWORD
	v_cndmask_b32_e32 v10, v28, v29, vcc
	v_cmp_lt_i32_e32 vcc, -1, v8
	v_bitop3_b32 v20, v10, s23, v9 bitop3:0xde
	v_and_b32_e32 v8, 0xffffff00, v8
	v_cndmask_b32_e32 v9, v28, v29, vcc
	v_bitop3_b32 v21, v9, s82, v8 bitop3:0xde
	v_pk_add_f32 v[8:9], v[14:15], v[6:7] op_sel_hi:[0,1]
	v_cmp_lt_i32_e32 vcc, -1, v9
	v_and_b32_e32 v9, 0xffffff00, v9
	v_max_u32_e32 v84, v12, v13
	v_cndmask_b32_e32 v10, v28, v29, vcc
	v_cmp_lt_i32_e32 vcc, -1, v8
	v_bitop3_b32 v14, v10, s83, v9 bitop3:0xde
	v_and_b32_e32 v8, 0xffffff00, v8
	v_cndmask_b32_e32 v9, v28, v29, vcc
	v_bitop3_b32 v79, v9, s44, v8 bitop3:0xde
	v_pk_add_f32 v[8:9], v[16:17], v[6:7] op_sel_hi:[0,1]
	v_cmp_lt_i32_e32 vcc, -1, v9
	v_and_b32_e32 v9, 0xffffff00, v9
	v_min_u32_e32 v12, v12, v13
	v_cndmask_b32_e32 v10, v28, v29, vcc
	v_cmp_lt_i32_e32 vcc, -1, v8
	v_bitop3_b32 v16, v10, s45, v9 bitop3:0xde
	v_and_b32_e32 v8, 0xffffff00, v8
	v_cndmask_b32_e32 v9, v28, v29, vcc
	v_bitop3_b32 v80, v9, s33, v8 bitop3:0xde
	v_pk_add_f32 v[8:9], v[18:19], v[6:7] op_sel_hi:[0,1]
	v_cmp_lt_i32_e32 vcc, -1, v9
	v_and_b32_e32 v9, 0xffffff00, v9
	v_and_b32_sdwa v10, v32, s57 dst_sel:DWORD dst_unused:UNUSED_PAD src0_sel:WORD_1 src1_sel:DWORD
	v_cndmask_b32_e32 v6, v28, v29, vcc
	v_cmp_lt_i32_e32 vcc, -1, v8
	v_bitop3_b32 v18, v6, s87, v9 bitop3:0xde
	v_and_b32_sdwa v9, v33, s57 dst_sel:DWORD dst_unused:UNUSED_PAD src0_sel:WORD_1 src1_sel:DWORD
	v_cndmask_b32_e32 v6, v28, v29, vcc
	v_cmp_gt_i32_e32 vcc, 0, v33
	v_and_b32_e32 v8, 0xffffff00, v8
	v_xor_b32_sdwa v33, v30, v27 dst_sel:DWORD dst_unused:UNUSED_PAD src0_sel:WORD_1 src1_sel:DWORD
	v_cndmask_b32_e32 v9, v11, v9, vcc
	v_cmp_gt_i32_e32 vcc, 0, v32
	v_cvt_f32_f16_e32 v11, v9
	v_bitop3_b32 v32, v6, s2, v8 bitop3:0xde
	v_cndmask_b32_e32 v10, v81, v10, vcc
	v_cvt_f32_f16_e32 v10, v10
	v_mov_b32_e32 v6, v7
	v_max_u32_e32 v13, v20, v21
	v_min_u32_e32 v20, v20, v21
; DI unsigned candkey(float s, int pos) { const unsigned b = __float_as_uint(s); const unsigned o = (b >> 31) ? ~b : (b ^ 0x80000000u); return (o & 0xffffff00u) | (unsigned)(255 - pos); }
; DI void phase10(const Params& P, char* smem) {
;     ...
;     C2[0] = candkey(v1[3] + v2[3], 51);
;     C2[1] = candkey(v1[4] + v2[0], 64);
;     C2[2] = candkey(v1[4] + v2[1], 65);
;     C2[3] = candkey(v1[4] + v2[2], 66);
;     C2[4] = candkey(v1[5] + v2[0], 80);
;     C2[5] = candkey(v1[5] + v2[1], 81);
;     C2[6] = candkey(v1[6] + v2[0], 96);
;     C2[7] = candkey(v1[6] + v2[1], 97);
;     C2[8] = candkey(v1[7] + v2[0], 112);
;     C2[9] = candkey(v1[7] + v2[1], 113);
;     C2[10] = candkey(v1[8] + v2[0], 128);
;     C2[11] = candkey(v1[9] + v2[0], 144);
;     C2[12] = candkey(v1[10] + v2[0], 160);
;     C2[13] = candkey(v1[11] + v2[0], 176);
;     C2[14] = candkey(v1[12] + v2[0], 192);
;     C2[15] = candkey(v1[13] + v2[0], 208);
;     C3[0] = candkey(v1[14] + v2[0], 224);
;     C3[1] = candkey(v1[15] + v2[0], 240);
;     C3[2] = 0u;
;     C3[3] = 0u;
;     C3[4] = 0u;
;     C3[5] = 0u;
;     C3[6] = 0u;
;     C3[7] = 0u;
;     C3[8] = 0u;
;     C3[9] = 0u;
;     C3[10] = 0u;
;     C3[11] = 0u;
;     C3[12] = 0u;
;     C3[13] = 0u;
;     C3[14] = 0u;
;     C3[15] = 0u;
;     SORT16(C1) SORT16(C2) SORT16(C3)
	v_pk_add_f32 v[8:9], v[6:7], v[10:11] op_sel_hi:[0,1]
	v_cmp_lt_i32_e32 vcc, -1, v9
	v_and_b32_e32 v9, 0xffffff00, v9
	v_xor_b32_sdwa v11, v31, v27 dst_sel:DWORD dst_unused:UNUSED_PAD src0_sel:WORD_1 src1_sel:DWORD
	v_cndmask_b32_e32 v7, v28, v29, vcc
	v_bitop3_b32 v7, v7, s0, v9 bitop3:0xde
	v_and_b32_sdwa v9, v31, s57 dst_sel:DWORD dst_unused:UNUSED_PAD src0_sel:WORD_1 src1_sel:DWORD
	v_cmp_gt_i32_e32 vcc, 0, v31
	v_and_b32_sdwa v10, v30, s57 dst_sel:DWORD dst_unused:UNUSED_PAD src0_sel:WORD_1 src1_sel:DWORD
	v_pk_add_f32 v[4:5], v[4:5], v[6:7] op_sel_hi:[1,0]
	v_cndmask_b32_e32 v9, v11, v9, vcc
	v_cmp_gt_i32_e32 vcc, 0, v30
	v_cvt_f32_f16_e32 v11, v9
	v_max_u32_e32 v21, v14, v79
	v_cndmask_b32_e32 v10, v33, v10, vcc
	v_cvt_f32_f16_e32 v10, v10
	v_cmp_lt_i32_e32 vcc, -1, v8
	v_and_b32_e32 v8, 0xffffff00, v8
	v_xor_b32_sdwa v33, v1, v27 dst_sel:DWORD dst_unused:UNUSED_PAD src0_sel:WORD_1 src1_sel:DWORD
	v_cndmask_b32_e32 v9, v28, v29, vcc
	v_bitop3_b32 v30, v9, s88, v8 bitop3:0xde
	v_pk_add_f32 v[8:9], v[6:7], v[10:11] op_sel_hi:[0,1]
	v_cmp_lt_i32_e32 vcc, -1, v9
	v_and_b32_e32 v9, 0xffffff00, v9
	v_xor_b32_sdwa v11, v3, v27 dst_sel:DWORD dst_unused:UNUSED_PAD src0_sel:WORD_1 src1_sel:DWORD
	v_cndmask_b32_e32 v10, v28, v29, vcc
	v_bitop3_b32 v31, v10, s89, v9 bitop3:0xde
	v_and_b32_sdwa v9, v3, s57 dst_sel:DWORD dst_unused:UNUSED_PAD src0_sel:WORD_1 src1_sel:DWORD
	v_cmp_gt_i32_e32 vcc, 0, v3
	v_and_b32_sdwa v10, v1, s57 dst_sel:DWORD dst_unused:UNUSED_PAD src0_sel:WORD_1 src1_sel:DWORD
	v_min_u32_e32 v14, v14, v79
	v_cndmask_b32_e32 v3, v11, v9, vcc
	v_cmp_gt_i32_e32 vcc, 0, v1
	v_cvt_f32_f16_e32 v11, v3
	v_and_b32_e32 v3, 0xffffff00, v8
	v_cndmask_b32_e32 v1, v33, v10, vcc
	v_cvt_f32_f16_e32 v10, v1
	v_cmp_lt_i32_e32 vcc, -1, v8
	v_max_u32_e32 v33, v67, v66
	v_min_u32_e32 v66, v67, v66
	v_pk_add_f32 v[8:9], v[6:7], v[10:11] op_sel_hi:[0,1]
	v_cndmask_b32_e32 v1, v28, v29, vcc
	v_cmp_lt_i32_e32 vcc, -1, v9
	v_bitop3_b32 v1, v1, s90, v3 bitop3:0xde
	v_and_b32_e32 v9, 0xffffff00, v9
	v_cndmask_b32_e32 v3, v28, v29, vcc
	v_cmp_lt_i32_e32 vcc, -1, v8
	v_bitop3_b32 v3, v3, 63, v9 bitop3:0xde
	v_and_b32_e32 v8, 0xffffff00, v8
	v_cndmask_b32_e32 v9, v28, v29, vcc
	v_cmp_lt_i32_e32 vcc, -1, v5
	v_and_b32_e32 v5, 0xffffff00, v5
	v_bitop3_b32 v8, v9, 47, v8 bitop3:0xde
	v_cndmask_b32_e32 v6, v28, v29, vcc
	v_cmp_lt_i32_e32 vcc, -1, v4
	v_bitop3_b32 v5, v6, 31, v5 bitop3:0xde
	v_and_b32_e32 v4, 0xffffff00, v4
	v_cndmask_b32_e32 v6, v28, v29, vcc
	v_bitop3_b32 v4, v6, 15, v4 bitop3:0xde
	v_max_u32_e32 v6, v69, v70
	v_min_u32_e32 v9, v69, v70
	v_max_u32_e32 v10, v71, v72
	v_min_u32_e32 v11, v71, v72
	v_max_u32_e32 v67, v64, v73
	v_min_u32_e32 v64, v64, v73
	v_max_u32_e32 v69, v74, v75
	v_min_u32_e32 v70, v74, v75
	v_max_u32_e32 v71, v76, v77
	v_min_u32_e32 v72, v76, v77
	v_max_u32_e32 v73, v22, v78
	v_min_u32_e32 v22, v22, v78
	v_max_u32_e32 v74, v25, v24
	v_min_u32_e32 v24, v25, v24
	v_max_u32_e32 v25, v6, v10
	v_min_u32_e32 v6, v6, v10
	v_max_u32_e32 v10, v9, v11
	v_min_u32_e32 v9, v9, v11
	v_max_u32_e32 v11, v33, v67
	v_min_u32_e32 v33, v33, v67
	v_max_u32_e32 v67, v66, v64
	v_min_u32_e32 v64, v66, v64
	v_max_u32_e32 v66, v69, v71
	v_min_u32_e32 v69, v69, v71
	v_max_u32_e32 v71, v70, v72
	v_min_u32_e32 v70, v70, v72
	v_max_u32_e32 v72, v73, v74
	v_min_u32_e32 v73, v73, v74
	v_max_u32_e32 v74, v22, v24
	v_min_u32_e32 v22, v22, v24
	v_max_u32_e32 v24, v10, v6
	v_min_u32_e32 v6, v10, v6
	v_max_u32_e32 v10, v67, v33
	v_min_u32_e32 v33, v67, v33
	v_max_u32_e32 v67, v71, v69
	v_min_u32_e32 v69, v71, v69
	v_max_u32_e32 v71, v74, v73
	v_min_u32_e32 v73, v74, v73
	v_max_u32_e32 v74, v25, v11
	v_min_u32_e32 v11, v25, v11
	v_max_u32_e32 v25, v24, v10
	v_min_u32_e32 v10, v24, v10
	v_max_u32_e32 v24, v6, v33
	v_min_u32_e32 v6, v6, v33
	v_max_u32_e32 v33, v9, v64
	v_min_u32_e32 v9, v9, v64
	v_max_u32_e32 v64, v66, v72
	v_min_u32_e32 v66, v66, v72
	v_max_u32_e32 v72, v67, v71
	v_min_u32_e32 v67, v67, v71
	v_max_u32_e32 v71, v69, v73
	v_min_u32_e32 v69, v69, v73
	v_max_u32_e32 v73, v70, v22
	v_min_u32_e32 v22, v70, v22
	v_max_u32_e32 v70, v24, v11
	v_min_u32_e32 v11, v24, v11
	v_max_u32_e32 v24, v33, v10
	v_min_u32_e32 v10, v33, v10
	v_max_u32_e32 v33, v71, v66
	v_min_u32_e32 v66, v71, v66
	v_max_u32_e32 v71, v73, v67
	v_min_u32_e32 v67, v73, v67
	v_max_u32_e32 v73, v25, v70
	v_min_u32_e32 v25, v25, v70
	v_max_u32_e32 v70, v24, v11
	v_min_u32_e32 v11, v24, v11
	v_max_u32_e32 v24, v10, v6
	v_min_u32_e32 v6, v10, v6
	v_max_u32_e32 v10, v72, v33
	v_min_u32_e32 v33, v72, v33
	v_max_u32_e32 v72, v71, v66
	v_min_u32_e32 v66, v71, v66
	v_max_u32_e32 v71, v67, v69
	v_min_u32_e32 v67, v67, v69
	v_max_u32_e32 v79, v16, v80
	v_min_u32_e32 v16, v16, v80
	v_max_u32_e32 v80, v18, v32
	v_min_u32_e32 v18, v18, v32
	v_max_u32_e32 v32, v7, v30
	v_min_u32_e32 v7, v7, v30
	v_max_u32_e32 v30, v31, v1
	v_min_u32_e32 v1, v31, v1
	v_max_u32_e32 v31, v3, v8
	v_min_u32_e32 v3, v3, v8
	v_min_u32_e32 v69, v74, v64
	v_max_u32_e32 v75, v73, v10
	v_min_u32_e32 v10, v73, v10
	v_max_u32_e32 v73, v25, v33
	v_min_u32_e32 v25, v25, v33
	v_max_u32_e32 v33, v70, v72
	v_min_u32_e32 v70, v70, v72
	v_max_u32_e32 v72, v11, v66
	v_min_u32_e32 v11, v11, v66
	v_max_u32_e32 v66, v24, v71
	v_min_u32_e32 v24, v24, v71
	v_max_u32_e32 v71, v6, v67
	v_min_u32_e32 v6, v6, v67
	v_max_u32_e32 v67, v9, v22
	v_max_u32_e32 v8, v84, v13
	v_min_u32_e32 v13, v84, v13
	v_max_u32_e32 v84, v12, v20
	v_min_u32_e32 v12, v12, v20
	v_max_u32_e32 v20, v21, v79
	v_min_u32_e32 v21, v21, v79
	v_max_u32_e32 v79, v14, v16
	v_min_u32_e32 v14, v14, v16
	v_max_u32_e32 v16, v80, v32
	v_min_u32_e32 v32, v80, v32
	v_max_u32_e32 v80, v18, v7
; DI void phase10(const Params& P, char* smem) {
;     ...
;     SORT16(C1) SORT16(C2) SORT16(C3)
;     MERGE16(C0, C1) MERGE16(C0, C2) MERGE16(C0, C3)
	v_min_u32_e32 v7, v18, v7
	v_max_u32_e32 v18, v30, v31
	v_min_u32_e32 v30, v30, v31
	v_max_u32_e32 v31, v1, v3
	v_min_u32_e32 v9, v9, v22
	v_max_u32_e32 v22, v72, v69
	v_min_u32_e32 v69, v72, v69
	v_max_u32_e32 v72, v66, v10
	v_min_u32_e32 v10, v66, v10
	v_max_u32_e32 v66, v71, v25
	v_min_u32_e32 v25, v71, v25
	v_max_u32_e32 v71, v67, v70
	v_min_u32_e32 v67, v67, v70
	v_min_u32_e32 v1, v1, v3
	v_max_u32_e32 v3, v84, v13
	v_min_u32_e32 v13, v84, v13
	v_max_u32_e32 v84, v79, v21
	v_min_u32_e32 v21, v79, v21
	v_max_u32_e32 v79, v80, v32
	v_min_u32_e32 v32, v80, v32
	v_max_u32_e32 v80, v31, v30
	v_min_u32_e32 v30, v31, v30
	v_max_u32_e32 v70, v73, v22
	v_min_u32_e32 v22, v73, v22
	v_max_u32_e32 v73, v33, v72
	v_min_u32_e32 v33, v33, v72
	v_max_u32_e32 v72, v66, v69
	v_min_u32_e32 v66, v66, v69
	v_max_u32_e32 v69, v71, v10
	v_min_u32_e32 v10, v71, v10
	v_max_u32_e32 v71, v25, v11
	v_min_u32_e32 v11, v25, v11
	v_max_u32_e32 v25, v67, v24
	v_min_u32_e32 v24, v67, v24
	v_max_u32_e32 v31, v8, v20
	v_min_u32_e32 v8, v8, v20
	v_max_u32_e32 v20, v3, v84
	v_min_u32_e32 v3, v3, v84
	v_max_u32_e32 v84, v13, v21
	v_min_u32_e32 v13, v13, v21
	v_max_u32_e32 v21, v12, v14
	v_min_u32_e32 v12, v12, v14
	v_max_u32_e32 v14, v16, v18
	v_min_u32_e32 v16, v16, v18
	v_max_u32_e32 v18, v79, v80
	v_min_u32_e32 v79, v79, v80
	v_max_u32_e32 v80, v32, v30
	v_min_u32_e32 v30, v32, v30
	v_max_u32_e32 v32, v7, v1
	v_min_u32_e32 v67, v75, v70
	v_min_u32_e32 v76, v73, v22
	v_min_u32_e32 v77, v33, v72
	v_min_u32_e32 v78, v69, v66
	v_min_u32_e32 v81, v10, v71
	v_min_u32_e32 v82, v25, v11
	v_min_u32_e32 v83, v24, v6
	v_min_u32_e32 v1, v7, v1
	v_max_u32_e32 v7, v84, v8
	v_min_u32_e32 v8, v84, v8
	v_max_u32_e32 v84, v21, v3
	v_min_u32_e32 v3, v21, v3
	v_max_u32_e32 v21, v80, v16
	v_min_u32_e32 v16, v80, v16
	v_max_u32_e32 v80, v32, v79
	v_min_u32_e32 v32, v32, v79
	v_max_u32_e32 v79, v20, v7
	v_min_u32_e32 v7, v20, v7
	v_max_u32_e32 v20, v84, v8
	v_min_u32_e32 v8, v84, v8
	v_max_u32_e32 v84, v3, v13
	v_min_u32_e32 v3, v3, v13
	v_max_u32_e32 v13, v18, v21
	v_min_u32_e32 v18, v18, v21
	v_max_u32_e32 v21, v80, v16
	v_min_u32_e32 v16, v80, v16
	v_max_u32_e32 v80, v32, v30
	v_min_u32_e32 v30, v32, v30
	v_max_u32_e32 v9, v35, v9
	v_max_u32_e32 v35, v36, v83
	v_max3_u32 v6, v37, v24, v6
	v_max_u32_e32 v24, v38, v82
	v_max3_u32 v11, v39, v25, v11
	v_max_u32_e32 v25, v40, v81
	v_max3_u32 v10, v41, v10, v71
	v_max_u32_e32 v36, v57, v78
	v_max3_u32 v37, v58, v69, v66
	v_max_u32_e32 v38, v59, v77
	v_max3_u32 v33, v60, v33, v72
	v_max_u32_e32 v39, v61, v76
	v_max3_u32 v22, v62, v73, v22
	v_max_u32_e32 v40, v63, v67
	v_max3_u32 v41, v65, v75, v70
	v_max3_u32 v57, v68, v74, v64
	v_min_u32_e32 v32, v31, v14
	v_max_u32_e32 v85, v79, v13
	v_min_u32_e32 v13, v79, v13
	v_max_u32_e32 v79, v7, v18
	v_min_u32_e32 v7, v7, v18
	v_max_u32_e32 v18, v20, v21
	v_min_u32_e32 v20, v20, v21
	v_max_u32_e32 v21, v8, v16
	v_min_u32_e32 v8, v8, v16
	v_max_u32_e32 v16, v84, v80
	v_min_u32_e32 v80, v84, v80
	v_max_u32_e32 v84, v3, v30
	v_min_u32_e32 v3, v3, v30
	v_max_u32_e32 v30, v12, v1
	v_max_u32_e32 v58, v9, v37
	v_min_u32_e32 v9, v9, v37
	v_max_u32_e32 v37, v35, v38
	v_min_u32_e32 v35, v35, v38
	v_max_u32_e32 v38, v6, v33
	v_min_u32_e32 v6, v6, v33
	v_max_u32_e32 v33, v24, v39
	v_min_u32_e32 v24, v24, v39
	v_max_u32_e32 v39, v11, v22
	v_min_u32_e32 v11, v11, v22
	v_max_u32_e32 v22, v25, v40
	v_min_u32_e32 v25, v25, v40
	v_max_u32_e32 v40, v10, v41
	v_min_u32_e32 v10, v10, v41
	v_max_u32_e32 v41, v36, v57
	v_min_u32_e32 v36, v36, v57
	v_min_u32_e32 v1, v12, v1
	v_max_u32_e32 v12, v21, v32
	v_min_u32_e32 v21, v21, v32
	v_max_u32_e32 v32, v16, v13
	v_min_u32_e32 v13, v16, v13
	v_max_u32_e32 v16, v84, v7
	v_min_u32_e32 v7, v84, v7
	v_max_u32_e32 v84, v30, v20
	v_min_u32_e32 v20, v30, v20
	v_max_u32_e32 v57, v58, v39
	v_min_u32_e32 v39, v58, v39
	v_max_u32_e32 v58, v37, v22
	v_min_u32_e32 v22, v37, v22
	v_max_u32_e32 v37, v38, v40
	v_min_u32_e32 v38, v38, v40
	v_max_u32_e32 v40, v33, v41
	v_min_u32_e32 v33, v33, v41
	v_max_u32_e32 v41, v9, v11
	v_min_u32_e32 v9, v9, v11
	v_max_u32_e32 v11, v35, v25
	v_min_u32_e32 v25, v35, v25
	v_max_u32_e32 v35, v6, v10
	v_min_u32_e32 v6, v6, v10
	v_max_u32_e32 v10, v24, v36
	v_min_u32_e32 v24, v24, v36
	v_max_u32_e32 v30, v79, v12
	v_min_u32_e32 v12, v79, v12
	v_max_u32_e32 v79, v18, v32
	v_min_u32_e32 v18, v18, v32
	v_max_u32_e32 v32, v16, v21
	v_min_u32_e32 v16, v16, v21
	v_max_u32_e32 v21, v84, v13
; DI unsigned lut4(const unsigned (&W)[4], int a) { const int j = a >> 2; const unsigned w = j == 0 ? W[0] : (j == 1 ? W[1] : (j == 2 ? W[2] : W[3])); return (w >> ((a & 3) * 8)) & 0xffu; }
; DI void phase10(const Params& P, char* smem) {
;     ...
;     MERGE16(C0, C1) MERGE16(C0, C2) MERGE16(C0, C3)
;     float e[16]; int te[16]; float sum = 0.f;
;     const float tv0 = [&]() { const unsigned o = C0[0] & 0xffffff00u; return __uint_as_float((o >> 31) ? (o ^ 0x80000000u) : ~o); }();
; #pragma unroll
;     for (int k = 0; k < 16; ++k) {
;       const unsigned key = C0[k]; const unsigned o = key & 0xffffff00u;
;       const float val = __uint_as_float((o >> 31) ? (o ^ 0x80000000u) : ~o);
;       const int pos = 255 - (int)(key & 255u);
;       te[k] = (int)(lut4(W1, pos >> 4) * 128u + lut4(W2, pos & 15));
	v_min_u32_e32 v13, v84, v13
	v_max_u32_e32 v84, v7, v8
	v_min_u32_e32 v7, v7, v8
	v_max_u32_e32 v8, v20, v80
	v_min_u32_e32 v20, v20, v80
	v_max_u32_e32 v36, v57, v37
	v_min_u32_e32 v37, v57, v37
	v_max_u32_e32 v57, v58, v40
	v_min_u32_e32 v40, v58, v40
	v_max_u32_e32 v58, v39, v38
	v_min_u32_e32 v38, v39, v38
	v_max_u32_e32 v39, v22, v33
	v_min_u32_e32 v22, v22, v33
	v_max_u32_e32 v33, v41, v35
	v_min_u32_e32 v35, v41, v35
	v_max_u32_e32 v41, v11, v10
	v_min_u32_e32 v10, v11, v10
	v_max_u32_e32 v11, v9, v6
	v_min_u32_e32 v6, v9, v6
	v_max_u32_e32 v9, v25, v24
	v_min_u32_e32 v24, v25, v24
	v_max_u32_e32 v80, v85, v30
	v_min_u32_e32 v30, v85, v30
	v_max_u32_e32 v85, v79, v12
	v_min_u32_e32 v12, v79, v12
	v_max_u32_e32 v79, v18, v32
	v_min_u32_e32 v18, v18, v32
	v_max_u32_e32 v32, v21, v16
	v_min_u32_e32 v16, v21, v16
	v_max_u32_e32 v21, v13, v84
	v_min_u32_e32 v13, v13, v84
	v_max_u32_e32 v84, v8, v7
	v_min_u32_e32 v7, v8, v7
	v_max_u32_e32 v8, v20, v3
	v_min_u32_e32 v3, v20, v3
	v_min_u32_e32 v25, v36, v57
	v_min_u32_e32 v59, v37, v40
	v_min_u32_e32 v60, v58, v39
	v_min_u32_e32 v61, v38, v22
	v_min_u32_e32 v62, v33, v41
	v_min_u32_e32 v63, v35, v10
	v_min_u32_e32 v64, v11, v9
	v_min_u32_e32 v65, v6, v24
	v_max3_u32 v1, v36, v57, v1
	v_max_u32_e32 v3, v25, v3
	v_max3_u32 v8, v37, v40, v8
	v_max_u32_e32 v7, v59, v7
	v_max3_u32 v25, v58, v39, v84
	v_max_u32_e32 v13, v60, v13
	v_max3_u32 v21, v38, v22, v21
	v_max_u32_e32 v16, v61, v16
	v_max3_u32 v22, v33, v41, v32
	v_max_u32_e32 v18, v62, v18
	v_max3_u32 v10, v35, v10, v79
	v_max_u32_e32 v12, v63, v12
	v_max3_u32 v9, v11, v9, v85
	v_max_u32_e32 v11, v64, v30
	v_max3_u32 v6, v6, v24, v80
	v_max3_u32 v14, v65, v31, v14
	v_max_u32_e32 v24, v1, v22
	v_min_u32_e32 v1, v1, v22
	v_max_u32_e32 v22, v3, v18
	v_min_u32_e32 v3, v3, v18
	v_max_u32_e32 v18, v8, v10
	v_min_u32_e32 v8, v8, v10
	v_max_u32_e32 v10, v7, v12
	v_min_u32_e32 v7, v7, v12
	v_max_u32_e32 v12, v25, v9
	v_min_u32_e32 v9, v25, v9
	v_max_u32_e32 v25, v13, v11
	v_min_u32_e32 v11, v13, v11
	v_max_u32_e32 v13, v21, v6
	v_min_u32_e32 v6, v21, v6
	v_max_u32_e32 v21, v16, v14
	v_min_u32_e32 v14, v16, v14
	v_max_u32_e32 v16, v24, v12
	v_min_u32_e32 v12, v24, v12
	v_max_u32_e32 v24, v22, v25
	v_min_u32_e32 v22, v22, v25
	v_max_u32_e32 v25, v18, v13
	v_min_u32_e32 v13, v18, v13
	v_max_u32_e32 v18, v10, v21
	v_min_u32_e32 v10, v10, v21
	v_max_u32_e32 v21, v1, v9
	v_min_u32_e32 v1, v1, v9
	v_max_u32_e32 v9, v3, v11
	v_min_u32_e32 v3, v3, v11
	v_max_u32_e32 v11, v8, v6
	v_min_u32_e32 v6, v8, v6
	v_max_u32_e32 v8, v7, v14
	v_min_u32_e32 v7, v7, v14
	v_max_u32_e32 v14, v16, v25
	v_min_u32_e32 v16, v16, v25
	v_max_u32_e32 v25, v24, v18
	v_min_u32_e32 v18, v24, v18
	v_max_u32_e32 v24, v12, v13
	v_min_u32_e32 v12, v12, v13
	v_max_u32_e32 v13, v22, v10
	v_min_u32_e32 v10, v22, v10
	v_max_u32_e32 v22, v21, v11
	v_min_u32_e32 v11, v21, v11
	v_max_u32_e32 v21, v9, v8
	v_min_u32_e32 v8, v9, v8
	v_max_u32_e32 v9, v1, v6
	v_min_u32_e32 v1, v1, v6
	v_max_u32_e32 v6, v3, v7
	v_min_u32_e32 v3, v3, v7
	v_min_u32_e32 v20, v5, v4
	v_max_u32_e32 v69, v9, v6
	v_min_u32_e32 v70, v9, v6
	v_min_u32_e32 v6, v1, v3
	v_max_u32_e32 v57, v14, v25
	v_min_u32_e32 v58, v14, v25
	v_max_u32_e32 v59, v16, v18
	v_min_u32_e32 v60, v16, v18
	v_max_u32_e32 v61, v24, v13
	v_min_u32_e32 v62, v24, v13
	v_max_u32_e32 v63, v12, v10
	v_min_u32_e32 v64, v12, v10
	v_max_u32_e32 v65, v22, v21
	v_min_u32_e32 v66, v22, v21
	v_max_u32_e32 v67, v11, v8
	v_min_u32_e32 v68, v11, v8
	v_max3_u32 v71, v1, v3, v20
	v_max3_u32 v72, v6, v5, v4
	v_max_u32_e32 v11, v57, v65
	v_max_u32_e32 v12, v58, v66
	v_max_u32_e32 v13, v59, v67
	v_max_u32_e32 v32, v60, v68
	v_max_u32_e32 v33, v61, v69
	v_max_u32_e32 v35, v62, v70
	v_max_u32_e32 v36, v63, v71
	v_max_u32_e32 v37, v64, v72
	v_max_u32_e32 v9, v11, v33
	v_max_u32_e32 v10, v12, v35
	v_max_u32_e32 v22, v13, v36
	v_max_u32_e32 v24, v32, v37
	v_max_u32_e32 v8, v9, v22
	v_max_u32_e32 v18, v10, v24
	v_max_u32_e32 v4, v8, v18
	v_bitop3_b32 v1, v4, s3, v4 bitop3:0xc
	v_cmp_lt_u32_e32 vcc, 63, v1
	v_mov_b32_e32 v3, v15
	s_and_saveexec_b64 s[0:1], vcc
	s_cbranch_execz .LBB0_1193
	v_lshrrev_b32_e32 v5, 6, v1
	v_cmp_lt_i32_e32 vcc, 1, v5
	s_mov_b64 s[6:7], 0
	s_and_saveexec_b64 s[8:9], vcc
	s_xor_b64 s[8:9], exec, s[8:9]
	s_cbranch_execnz .LBB0_1381
	s_or_saveexec_b64 s[8:9], s[8:9]
	v_mov_b32_e32 v3, v19
	s_xor_b64 exec, exec, s[8:9]
	s_cbranch_execnz .LBB0_1384
